# phase 7: next pair's ring prologue (addresses + 6 DMA units) issued before the SwiGLU epilogue, epilogue staging moved to ring slots 6-8, relaxed first waits
# baseline (speedup 1.0000x reference)
.Lgu2_tile:
	s_load_dwordx2 s[44:45], s[12:13], 0x160
	s_load_dwordx2 s[46:47], s[12:13], 0x130
	s_bfe_u32 s53, s21, 0x30006
	s_lshl_b32 s53, s53, 3
	s_and_b32 s56, s21, 7
	s_or_b32 s53, s53, s56
	s_lshl_b32 s53, s53, 7
	s_bfe_u32 s54, s21, 0x30003
	s_lshl_b32 s56, s55, 4
	s_add_i32 s54, s54, s56
	s_lshl_b32 s54, s54, 7
	v_lshrrev_b32_e32 v241, 6, v131
	v_and_b32_e32 v242, 63, v131
	s_nop 0
	v_readfirstlane_b32 s50, v241
	v_lshrrev_b32_e32 v241, 3, v242
	v_lshrrev_b32_e32 v243, 4, v242
	v_and_b32_e32 v244, 7, v242
	s_movk_i32 s56, 0x1080
	v_xor_b32_e32 v245, v244, v243
	v_lshlrev_b32_e32 v245, 4, v245
	v_mad_u32_u24 v228, v241, s56, v245
	v_or_b32_e32 v243, 4, v243
	v_xor_b32_e32 v245, v244, v243
	v_lshlrev_b32_e32 v245, 4, v245
	v_add_u32_e32 v241, 8, v241
	v_mad_u32_u24 v230, v241, s56, v245
	v_add_u32_e32 v229, 0x42000, v228
	v_add_u32_e32 v231, 0x42000, v230
	v_and_b32_e32 v241, 15, v242
	v_lshrrev_b32_e32 v243, 4, v242
	v_bfe_u32 v244, v242, 1, 3
	v_xor_b32_e32 v244, v243, v244
	v_lshlrev_b32_e32 v244, 4, v244
	v_lshl_or_b32 v232, v241, 7, v244
	v_xor_b32_e32 v233, 64, v232
	s_lshr_b32 s56, s50, 1
	s_and_b32 s57, s50, 1
	s_mul_i32 s0, s56, 64*528
	s_lshl_b32 s52, s57, 8
	s_add_i32 s0, s0, s52
	s_add_i32 s0, s0, 16
	v_mul_u32_u24_e32 v243, 4*528, v243
	v_lshl_add_u32 v243, v241, 2, v243
	v_add_u32_e32 v238, s0, v243
	s_add_i32 s22, s56, 0
	s_lshl_b32 s22, s22, 13
	s_add_i32 s22, s22, 16
	s_add_i32 s28, s57, 2
	s_lshl_b32 s28, s28, 13
	s_add_i32 s28, s28, 16
	s_add_i32 s40, s57, 4
	s_lshl_b32 s40, s40, 13
	s_add_i32 s40, s40, 16
	s_add_i32 s23, s56, 6
	s_lshl_b32 s23, s23, 13
	s_add_i32 s23, s23, 16
	s_add_i32 s29, s57, 8
	s_cmp_ge_u32 s29, 9
	s_cselect_b32 s0, 9, 0
	s_sub_i32 s29, s29, s0
	s_lshl_b32 s29, s29, 13
	s_add_i32 s29, s29, 16
	s_add_i32 s41, s57, 1
	s_lshl_b32 s41, s41, 13
	s_add_i32 s41, s41, 16
	s_add_i32 s24, s56, 3
	s_lshl_b32 s24, s24, 13
	s_add_i32 s24, s24, 16
	s_add_i32 s30, s57, 5
	s_lshl_b32 s30, s30, 13
	s_add_i32 s30, s30, 16
	s_add_i32 s42, s57, 7
	s_lshl_b32 s42, s42, 13
	s_add_i32 s42, s42, 16
	s_lshl_b32 s56, s50, 4
	s_add_i32 s57, s53, s56
	s_add_i32 s56, s54, s56
	s_mul_i32 s57, s57, 0x1080
	s_mul_i32 s56, s56, 0x1080
	s_waitcnt lgkmcnt(0)
	s_add_u32 s44, s44, s57
	s_addc_u32 s45, s45, 0
	s_add_u32 s46, s46, s56
	s_addc_u32 s47, s47, 0
	s_add_u32 s48, s46, 0x420000
	s_addc_u32 s49, s47, 0
	s_lshl_b32 s51, s50, 11
	s_add_i32 s51, s51, 16
	s_barrier
	s_mov_b32 m0, s51
	s_nop 0
	global_load_lds_dwordx4 v228, s[44:45]
	s_add_i32 m0, s51, 0x400
	s_nop 0
	global_load_lds_dwordx4 v230, s[44:45]
	s_add_i32 m0, s51, 0x2000
	s_nop 0
	global_load_lds_dwordx4 v229, s[44:45]
	s_add_i32 m0, s51, 0x2400
	s_nop 0
	global_load_lds_dwordx4 v231, s[44:45]
	s_add_i32 m0, s51, 0x4000
	s_nop 0
	global_load_lds_dwordx4 v228, s[46:47]
	s_add_i32 m0, s51, 0x4400
	s_nop 0
	global_load_lds_dwordx4 v230, s[46:47]
	s_add_i32 m0, s51, 0x6000
	s_nop 0
	global_load_lds_dwordx4 v229, s[46:47]
	s_add_i32 m0, s51, 0x6400
	s_nop 0
	global_load_lds_dwordx4 v231, s[46:47]
	s_add_i32 m0, s51, 0x8000
	s_nop 0
	global_load_lds_dwordx4 v228, s[48:49]
	s_add_i32 m0, s51, 0x8400
	s_nop 0
	global_load_lds_dwordx4 v230, s[48:49]
	s_add_i32 m0, s51, 0xa000
	s_nop 0
	global_load_lds_dwordx4 v229, s[48:49]
	s_add_i32 m0, s51, 0xa400
	s_nop 0
	global_load_lds_dwordx4 v231, s[48:49]
	v_add_u32_e32 v228, 0x80, v228
	v_add_u32_e32 v229, 0x80, v229
	v_add_u32_e32 v230, 0x80, v230
	v_add_u32_e32 v231, 0x80, v231
	v_mov_b32_e32 v2, 0
	v_mov_b32_e32 v3, 0
	v_mov_b32_e32 v4, 0
	v_mov_b32_e32 v5, 0
	v_mov_b32_e32 v6, 0
	v_mov_b32_e32 v7, 0
	v_mov_b32_e32 v8, 0
	v_mov_b32_e32 v9, 0
	v_mov_b32_e32 v10, 0
	v_mov_b32_e32 v11, 0
	v_mov_b32_e32 v12, 0
	v_mov_b32_e32 v13, 0
	v_mov_b32_e32 v14, 0
	v_mov_b32_e32 v15, 0
	v_mov_b32_e32 v16, 0
	v_mov_b32_e32 v17, 0
	v_mov_b32_e32 v18, 0
	v_mov_b32_e32 v19, 0
	v_mov_b32_e32 v20, 0
	v_mov_b32_e32 v21, 0
	v_mov_b32_e32 v22, 0
	v_mov_b32_e32 v23, 0
	v_mov_b32_e32 v24, 0
	v_mov_b32_e32 v25, 0
	v_mov_b32_e32 v26, 0
	v_mov_b32_e32 v27, 0
	v_mov_b32_e32 v28, 0
	v_mov_b32_e32 v29, 0
	v_mov_b32_e32 v30, 0
	v_mov_b32_e32 v31, 0
	v_mov_b32_e32 v32, 0
	v_mov_b32_e32 v33, 0
	v_mov_b32_e32 v34, 0
	v_mov_b32_e32 v35, 0
	v_mov_b32_e32 v36, 0
	v_mov_b32_e32 v37, 0
	v_mov_b32_e32 v38, 0
	v_mov_b32_e32 v39, 0
	v_mov_b32_e32 v40, 0
	v_mov_b32_e32 v41, 0
	v_mov_b32_e32 v42, 0
	v_mov_b32_e32 v43, 0
	v_mov_b32_e32 v44, 0
	v_mov_b32_e32 v45, 0
	v_mov_b32_e32 v46, 0
	v_mov_b32_e32 v47, 0
	v_mov_b32_e32 v48, 0
	v_mov_b32_e32 v49, 0
	v_mov_b32_e32 v50, 0
	v_mov_b32_e32 v51, 0
	v_mov_b32_e32 v52, 0
	v_mov_b32_e32 v53, 0
	v_mov_b32_e32 v54, 0
	v_mov_b32_e32 v55, 0
	v_mov_b32_e32 v56, 0
	v_mov_b32_e32 v57, 0
	v_mov_b32_e32 v58, 0
	v_mov_b32_e32 v59, 0
	v_mov_b32_e32 v60, 0
	v_mov_b32_e32 v61, 0
	v_mov_b32_e32 v62, 0
	v_mov_b32_e32 v63, 0
	v_mov_b32_e32 v64, 0
	v_mov_b32_e32 v65, 0
	v_mov_b32_e32 v66, 0
	v_mov_b32_e32 v67, 0
	v_mov_b32_e32 v68, 0
	v_mov_b32_e32 v69, 0
	v_mov_b32_e32 v70, 0
	v_mov_b32_e32 v71, 0
	v_mov_b32_e32 v72, 0
	v_mov_b32_e32 v73, 0
	v_mov_b32_e32 v74, 0
	v_mov_b32_e32 v75, 0
	v_mov_b32_e32 v76, 0
	v_mov_b32_e32 v77, 0
	v_mov_b32_e32 v78, 0
	v_mov_b32_e32 v79, 0
	v_mov_b32_e32 v80, 0
	v_mov_b32_e32 v81, 0
	v_mov_b32_e32 v82, 0
	v_mov_b32_e32 v83, 0
	v_mov_b32_e32 v84, 0
	v_mov_b32_e32 v85, 0
	v_mov_b32_e32 v86, 0
	v_mov_b32_e32 v87, 0
	v_mov_b32_e32 v88, 0
	v_mov_b32_e32 v89, 0
	v_mov_b32_e32 v90, 0
	v_mov_b32_e32 v91, 0
	v_mov_b32_e32 v92, 0
	v_mov_b32_e32 v93, 0
	v_mov_b32_e32 v94, 0
	v_mov_b32_e32 v95, 0
	v_mov_b32_e32 v96, 0
	v_mov_b32_e32 v97, 0
	v_mov_b32_e32 v98, 0
	v_mov_b32_e32 v99, 0
	v_mov_b32_e32 v100, 0
	v_mov_b32_e32 v101, 0
	v_mov_b32_e32 v102, 0
	v_mov_b32_e32 v103, 0
	v_mov_b32_e32 v104, 0
	v_mov_b32_e32 v105, 0
	v_mov_b32_e32 v106, 0
	v_mov_b32_e32 v107, 0
	v_mov_b32_e32 v108, 0
	v_mov_b32_e32 v109, 0
	v_mov_b32_e32 v110, 0
	v_mov_b32_e32 v111, 0
	v_mov_b32_e32 v112, 0
	v_mov_b32_e32 v113, 0
	v_mov_b32_e32 v114, 0
	v_mov_b32_e32 v115, 0
	v_mov_b32_e32 v116, 0
	v_mov_b32_e32 v117, 0
	v_mov_b32_e32 v118, 0
	v_mov_b32_e32 v119, 0
	v_mov_b32_e32 v120, 0
	v_mov_b32_e32 v121, 0
	v_mov_b32_e32 v122, 0
	v_mov_b32_e32 v123, 0
	v_mov_b32_e32 v124, 0
	v_mov_b32_e32 v125, 0
	v_mov_b32_e32 v126, 0
	v_mov_b32_e32 v127, 0
	v_mov_b32_e32 v128, 0
	v_mov_b32_e32 v129, 0
	s_load_dwordx2 s[56:57], s[12:13], 0x1d0
	v_bfe_u32 v241, v131, 4, 2
	s_lshr_b32 s0, s50, 1
	s_lshl_b32 s0, s0, 6
	s_add_i32 s0, s0, s53
	s_lshl_b32 s0, s0, 2
	v_lshlrev_b32_e32 v241, 4, v241
	s_waitcnt lgkmcnt(0)
	s_add_u32 s56, s56, s0
	s_addc_u32 s57, s57, 0
	global_load_dwordx4 v[152:155], v241, s[56:57]
	global_load_dwordx4 v[244:247], v241, s[56:57] offset:64
	global_load_dwordx4 v[248:251], v241, s[56:57] offset:128
	global_load_dwordx4 v[252:255], v241, s[56:57] offset:192
	s_waitcnt vmcnt(8)
.Lgu2_pair:
	s_barrier
	s_mov_b32 s52, 0

.Lgu2_loop_a0:
	v_add_u32_e32 v236, s40, v232
	v_add_u32_e32 v237, s40, v233
	ds_read_b128 v[188:191], v236
	ds_read_b128 v[196:199], v236 offset:2048
	ds_read_b128 v[200:203], v236 offset:4096
	ds_read_b128 v[204:207], v236 offset:6144
	ds_read_b128 v[212:215], v237
	ds_read_b128 v[216:219], v237 offset:2048
	ds_read_b128 v[220:223], v237 offset:4096
	ds_read_b128 v[224:227], v237 offset:6144
	s_mov_b32 m0, s51
	s_nop 0
	global_load_lds_dwordx4 v229, s[46:47]
	s_add_i32 m0, s51, 0x400
	s_nop 0
	global_load_lds_dwordx4 v231, s[46:47]
	s_add_i32 m0, s51, 0x2000
	s_nop 0
	global_load_lds_dwordx4 v228, s[48:49]
	s_add_i32 m0, s51, 0x2400
	s_nop 0
	global_load_lds_dwordx4 v230, s[48:49]
	s_add_i32 m0, s51, 0x4000
	s_nop 0
	global_load_lds_dwordx4 v229, s[48:49]
	s_add_i32 m0, s51, 0x4400
	s_nop 0
	global_load_lds_dwordx4 v231, s[48:49]
	s_waitcnt lgkmcnt(4)
	s_setprio 1
	v_mfma_f32_16x16x32_bf16 v[66:69], v[136:139], v[188:191], v[66:69]
	v_mfma_f32_16x16x32_bf16 v[70:73], v[136:139], v[196:199], v[70:73]
	v_mfma_f32_16x16x32_bf16 v[74:77], v[136:139], v[200:203], v[74:77]
	v_mfma_f32_16x16x32_bf16 v[78:81], v[136:139], v[204:207], v[78:81]
	v_mfma_f32_16x16x32_bf16 v[82:85], v[140:143], v[188:191], v[82:85]
	v_mfma_f32_16x16x32_bf16 v[86:89], v[140:143], v[196:199], v[86:89]
	v_mfma_f32_16x16x32_bf16 v[90:93], v[140:143], v[200:203], v[90:93]
	v_mfma_f32_16x16x32_bf16 v[94:97], v[140:143], v[204:207], v[94:97]
	v_mfma_f32_16x16x32_bf16 v[98:101], v[144:147], v[188:191], v[98:101]
	v_mfma_f32_16x16x32_bf16 v[102:105], v[144:147], v[196:199], v[102:105]
	v_mfma_f32_16x16x32_bf16 v[106:109], v[144:147], v[200:203], v[106:109]
	v_mfma_f32_16x16x32_bf16 v[110:113], v[144:147], v[204:207], v[110:113]
	v_mfma_f32_16x16x32_bf16 v[114:117], v[148:151], v[188:191], v[114:117]
	v_mfma_f32_16x16x32_bf16 v[118:121], v[148:151], v[196:199], v[118:121]
	v_mfma_f32_16x16x32_bf16 v[122:125], v[148:151], v[200:203], v[122:125]
	v_mfma_f32_16x16x32_bf16 v[126:129], v[148:151], v[204:207], v[126:129]
	s_waitcnt lgkmcnt(0)
	v_mfma_f32_16x16x32_bf16 v[66:69], v[172:175], v[212:215], v[66:69]
	v_mfma_f32_16x16x32_bf16 v[70:73], v[172:175], v[216:219], v[70:73]
	v_mfma_f32_16x16x32_bf16 v[74:77], v[172:175], v[220:223], v[74:77]
	v_mfma_f32_16x16x32_bf16 v[78:81], v[172:175], v[224:227], v[78:81]
	v_mfma_f32_16x16x32_bf16 v[82:85], v[176:179], v[212:215], v[82:85]
	v_mfma_f32_16x16x32_bf16 v[86:89], v[176:179], v[216:219], v[86:89]
	v_mfma_f32_16x16x32_bf16 v[90:93], v[176:179], v[220:223], v[90:93]
	v_mfma_f32_16x16x32_bf16 v[94:97], v[176:179], v[224:227], v[94:97]
	v_mfma_f32_16x16x32_bf16 v[98:101], v[180:183], v[212:215], v[98:101]
	v_mfma_f32_16x16x32_bf16 v[102:105], v[180:183], v[216:219], v[102:105]
	v_mfma_f32_16x16x32_bf16 v[106:109], v[180:183], v[220:223], v[106:109]
	v_mfma_f32_16x16x32_bf16 v[110:113], v[180:183], v[224:227], v[110:113]
	v_mfma_f32_16x16x32_bf16 v[114:117], v[184:187], v[212:215], v[114:117]
	v_mfma_f32_16x16x32_bf16 v[118:121], v[184:187], v[216:219], v[118:121]
	v_mfma_f32_16x16x32_bf16 v[122:125], v[184:187], v[220:223], v[122:125]
	v_mfma_f32_16x16x32_bf16 v[126:129], v[184:187], v[224:227], v[126:129]
	s_setprio 0
	v_add_u32_e32 v228, 0x80, v228
	v_add_u32_e32 v229, 0x80, v229
	v_add_u32_e32 v230, 0x80, v230
	v_add_u32_e32 v231, 0x80, v231
	s_waitcnt vmcnt(4)
	s_barrier
	v_add_u32_e32 v234, s23, v232
	v_add_u32_e32 v236, s29, v232
	v_add_u32_e32 v235, s23, v233
	v_add_u32_e32 v237, s29, v233
	ds_read_b128 v[136:139], v234
	ds_read_b128 v[140:143], v234 offset:2048
	ds_read_b128 v[144:147], v234 offset:4096
	ds_read_b128 v[148:151], v234 offset:6144
	ds_read_b128 v[188:191], v236
	ds_read_b128 v[196:199], v236 offset:2048
	ds_read_b128 v[200:203], v236 offset:4096
	ds_read_b128 v[204:207], v236 offset:6144
	ds_read_b128 v[172:175], v235
	ds_read_b128 v[176:179], v235 offset:2048
	ds_read_b128 v[180:183], v235 offset:4096
	ds_read_b128 v[184:187], v235 offset:6144
	ds_read_b128 v[212:215], v237
	ds_read_b128 v[216:219], v237 offset:2048
	ds_read_b128 v[220:223], v237 offset:4096
	ds_read_b128 v[224:227], v237 offset:6144
	s_add_i32 m0, s51, 0x6000
	s_nop 0
	global_load_lds_dwordx4 v228, s[44:45]
	s_add_i32 m0, s51, 0x6400
	s_nop 0
	global_load_lds_dwordx4 v230, s[44:45]
	s_add_i32 m0, s51, 0x8000
	s_nop 0
	global_load_lds_dwordx4 v229, s[44:45]
	s_add_i32 m0, s51, 0x8400
	s_nop 0
	global_load_lds_dwordx4 v231, s[44:45]
	s_add_i32 m0, s51, 0xa000
	s_nop 0
	global_load_lds_dwordx4 v228, s[46:47]
	s_add_i32 m0, s51, 0xa400
	s_nop 0
	global_load_lds_dwordx4 v230, s[46:47]
	s_waitcnt lgkmcnt(8)
	s_setprio 1
	v_mfma_f32_16x16x32_bf16 v[2:5], v[136:139], v[188:191], v[2:5]
	v_mfma_f32_16x16x32_bf16 v[6:9], v[136:139], v[196:199], v[6:9]
	v_mfma_f32_16x16x32_bf16 v[10:13], v[136:139], v[200:203], v[10:13]
	v_mfma_f32_16x16x32_bf16 v[14:17], v[136:139], v[204:207], v[14:17]
	v_mfma_f32_16x16x32_bf16 v[18:21], v[140:143], v[188:191], v[18:21]
	v_mfma_f32_16x16x32_bf16 v[22:25], v[140:143], v[196:199], v[22:25]
	v_mfma_f32_16x16x32_bf16 v[26:29], v[140:143], v[200:203], v[26:29]
	v_mfma_f32_16x16x32_bf16 v[30:33], v[140:143], v[204:207], v[30:33]
	v_mfma_f32_16x16x32_bf16 v[34:37], v[144:147], v[188:191], v[34:37]
	v_mfma_f32_16x16x32_bf16 v[38:41], v[144:147], v[196:199], v[38:41]
	v_mfma_f32_16x16x32_bf16 v[42:45], v[144:147], v[200:203], v[42:45]
	v_mfma_f32_16x16x32_bf16 v[46:49], v[144:147], v[204:207], v[46:49]
	v_mfma_f32_16x16x32_bf16 v[50:53], v[148:151], v[188:191], v[50:53]
	v_mfma_f32_16x16x32_bf16 v[54:57], v[148:151], v[196:199], v[54:57]
	v_mfma_f32_16x16x32_bf16 v[58:61], v[148:151], v[200:203], v[58:61]
	v_mfma_f32_16x16x32_bf16 v[62:65], v[148:151], v[204:207], v[62:65]
	s_waitcnt lgkmcnt(0)
	v_mfma_f32_16x16x32_bf16 v[2:5], v[172:175], v[212:215], v[2:5]
	v_mfma_f32_16x16x32_bf16 v[6:9], v[172:175], v[216:219], v[6:9]
	v_mfma_f32_16x16x32_bf16 v[10:13], v[172:175], v[220:223], v[10:13]
	v_mfma_f32_16x16x32_bf16 v[14:17], v[172:175], v[224:227], v[14:17]
	v_mfma_f32_16x16x32_bf16 v[18:21], v[176:179], v[212:215], v[18:21]
	v_mfma_f32_16x16x32_bf16 v[22:25], v[176:179], v[216:219], v[22:25]
	v_mfma_f32_16x16x32_bf16 v[26:29], v[176:179], v[220:223], v[26:29]
	v_mfma_f32_16x16x32_bf16 v[30:33], v[176:179], v[224:227], v[30:33]
	v_mfma_f32_16x16x32_bf16 v[34:37], v[180:183], v[212:215], v[34:37]
	v_mfma_f32_16x16x32_bf16 v[38:41], v[180:183], v[216:219], v[38:41]
	v_mfma_f32_16x16x32_bf16 v[42:45], v[180:183], v[220:223], v[42:45]
	v_mfma_f32_16x16x32_bf16 v[46:49], v[180:183], v[224:227], v[46:49]
	v_mfma_f32_16x16x32_bf16 v[50:53], v[184:187], v[212:215], v[50:53]
	v_mfma_f32_16x16x32_bf16 v[54:57], v[184:187], v[216:219], v[54:57]
	v_mfma_f32_16x16x32_bf16 v[58:61], v[184:187], v[220:223], v[58:61]
	v_mfma_f32_16x16x32_bf16 v[62:65], v[184:187], v[224:227], v[62:65]
	s_setprio 0
	s_waitcnt vmcnt(6)
	s_barrier
	v_add_u32_e32 v236, s41, v232
	v_add_u32_e32 v237, s41, v233
	ds_read_b128 v[188:191], v236
	ds_read_b128 v[196:199], v236 offset:2048
	ds_read_b128 v[200:203], v236 offset:4096
	ds_read_b128 v[204:207], v236 offset:6144
	ds_read_b128 v[212:215], v237
	ds_read_b128 v[216:219], v237 offset:2048
	ds_read_b128 v[220:223], v237 offset:4096
	ds_read_b128 v[224:227], v237 offset:6144
	s_add_i32 m0, s51, 0xc000
	s_nop 0
	global_load_lds_dwordx4 v229, s[46:47]
	s_add_i32 m0, s51, 0xc400
	s_nop 0
	global_load_lds_dwordx4 v231, s[46:47]
	s_add_i32 m0, s51, 0xe000
	s_nop 0
	global_load_lds_dwordx4 v228, s[48:49]
	s_add_i32 m0, s51, 0xe400
	s_nop 0
	global_load_lds_dwordx4 v230, s[48:49]
	s_add_i32 m0, s51, 0x10000
	s_nop 0
	global_load_lds_dwordx4 v229, s[48:49]
	s_add_i32 m0, s51, 0x10400
	s_nop 0
	global_load_lds_dwordx4 v231, s[48:49]
	s_waitcnt lgkmcnt(4)
	s_setprio 1
	v_mfma_f32_16x16x32_bf16 v[66:69], v[136:139], v[188:191], v[66:69]
	v_mfma_f32_16x16x32_bf16 v[70:73], v[136:139], v[196:199], v[70:73]
	v_mfma_f32_16x16x32_bf16 v[74:77], v[136:139], v[200:203], v[74:77]
	v_mfma_f32_16x16x32_bf16 v[78:81], v[136:139], v[204:207], v[78:81]
	v_mfma_f32_16x16x32_bf16 v[82:85], v[140:143], v[188:191], v[82:85]
	v_mfma_f32_16x16x32_bf16 v[86:89], v[140:143], v[196:199], v[86:89]
	v_mfma_f32_16x16x32_bf16 v[90:93], v[140:143], v[200:203], v[90:93]
	v_mfma_f32_16x16x32_bf16 v[94:97], v[140:143], v[204:207], v[94:97]
	v_mfma_f32_16x16x32_bf16 v[98:101], v[144:147], v[188:191], v[98:101]
	v_mfma_f32_16x16x32_bf16 v[102:105], v[144:147], v[196:199], v[102:105]
	v_mfma_f32_16x16x32_bf16 v[106:109], v[144:147], v[200:203], v[106:109]
	v_mfma_f32_16x16x32_bf16 v[110:113], v[144:147], v[204:207], v[110:113]
	v_mfma_f32_16x16x32_bf16 v[114:117], v[148:151], v[188:191], v[114:117]
	v_mfma_f32_16x16x32_bf16 v[118:121], v[148:151], v[196:199], v[118:121]
	v_mfma_f32_16x16x32_bf16 v[122:125], v[148:151], v[200:203], v[122:125]
	v_mfma_f32_16x16x32_bf16 v[126:129], v[148:151], v[204:207], v[126:129]
	s_waitcnt lgkmcnt(0)
	v_mfma_f32_16x16x32_bf16 v[66:69], v[172:175], v[212:215], v[66:69]
	v_mfma_f32_16x16x32_bf16 v[70:73], v[172:175], v[216:219], v[70:73]
	v_mfma_f32_16x16x32_bf16 v[74:77], v[172:175], v[220:223], v[74:77]
	v_mfma_f32_16x16x32_bf16 v[78:81], v[172:175], v[224:227], v[78:81]
	v_mfma_f32_16x16x32_bf16 v[82:85], v[176:179], v[212:215], v[82:85]
	v_mfma_f32_16x16x32_bf16 v[86:89], v[176:179], v[216:219], v[86:89]
	v_mfma_f32_16x16x32_bf16 v[90:93], v[176:179], v[220:223], v[90:93]
	v_mfma_f32_16x16x32_bf16 v[94:97], v[176:179], v[224:227], v[94:97]
	v_mfma_f32_16x16x32_bf16 v[98:101], v[180:183], v[212:215], v[98:101]
	v_mfma_f32_16x16x32_bf16 v[102:105], v[180:183], v[216:219], v[102:105]
	v_mfma_f32_16x16x32_bf16 v[106:109], v[180:183], v[220:223], v[106:109]
	v_mfma_f32_16x16x32_bf16 v[110:113], v[180:183], v[224:227], v[110:113]
	v_mfma_f32_16x16x32_bf16 v[114:117], v[184:187], v[212:215], v[114:117]
	v_mfma_f32_16x16x32_bf16 v[118:121], v[184:187], v[216:219], v[118:121]
	v_mfma_f32_16x16x32_bf16 v[122:125], v[184:187], v[220:223], v[122:125]
	v_mfma_f32_16x16x32_bf16 v[126:129], v[184:187], v[224:227], v[126:129]
	s_setprio 0
	v_add_u32_e32 v228, 0x80, v228
	v_add_u32_e32 v229, 0x80, v229
	v_add_u32_e32 v230, 0x80, v230
	v_add_u32_e32 v231, 0x80, v231
	s_waitcnt vmcnt(4)
	s_barrier
	v_add_u32_e32 v234, s24, v232
	v_add_u32_e32 v236, s30, v232
	v_add_u32_e32 v235, s24, v233
	v_add_u32_e32 v237, s30, v233
	ds_read_b128 v[136:139], v234
	ds_read_b128 v[140:143], v234 offset:2048
	ds_read_b128 v[144:147], v234 offset:4096
	ds_read_b128 v[148:151], v234 offset:6144
	ds_read_b128 v[188:191], v236
	ds_read_b128 v[196:199], v236 offset:2048
	ds_read_b128 v[200:203], v236 offset:4096
	ds_read_b128 v[204:207], v236 offset:6144
	ds_read_b128 v[172:175], v235
	ds_read_b128 v[176:179], v235 offset:2048
	ds_read_b128 v[180:183], v235 offset:4096
	ds_read_b128 v[184:187], v235 offset:6144
	ds_read_b128 v[212:215], v237
	ds_read_b128 v[216:219], v237 offset:2048
	ds_read_b128 v[220:223], v237 offset:4096
	ds_read_b128 v[224:227], v237 offset:6144
	s_mov_b32 m0, s51
	s_nop 0
	global_load_lds_dwordx4 v228, s[44:45]
	s_add_i32 m0, s51, 0x400
	s_nop 0
	global_load_lds_dwordx4 v230, s[44:45]
	s_add_i32 m0, s51, 0x2000
	s_nop 0
	global_load_lds_dwordx4 v229, s[44:45]
	s_add_i32 m0, s51, 0x2400
	s_nop 0
	global_load_lds_dwordx4 v231, s[44:45]
	s_add_i32 m0, s51, 0x4000
	s_nop 0
	global_load_lds_dwordx4 v228, s[46:47]
	s_add_i32 m0, s51, 0x4400
	s_nop 0
	global_load_lds_dwordx4 v230, s[46:47]
	s_waitcnt lgkmcnt(8)
	s_setprio 1
	v_mfma_f32_16x16x32_bf16 v[2:5], v[136:139], v[188:191], v[2:5]
	v_mfma_f32_16x16x32_bf16 v[6:9], v[136:139], v[196:199], v[6:9]
	v_mfma_f32_16x16x32_bf16 v[10:13], v[136:139], v[200:203], v[10:13]
	v_mfma_f32_16x16x32_bf16 v[14:17], v[136:139], v[204:207], v[14:17]
	v_mfma_f32_16x16x32_bf16 v[18:21], v[140:143], v[188:191], v[18:21]
	v_mfma_f32_16x16x32_bf16 v[22:25], v[140:143], v[196:199], v[22:25]
	v_mfma_f32_16x16x32_bf16 v[26:29], v[140:143], v[200:203], v[26:29]
	v_mfma_f32_16x16x32_bf16 v[30:33], v[140:143], v[204:207], v[30:33]
	v_mfma_f32_16x16x32_bf16 v[34:37], v[144:147], v[188:191], v[34:37]
	v_mfma_f32_16x16x32_bf16 v[38:41], v[144:147], v[196:199], v[38:41]
	v_mfma_f32_16x16x32_bf16 v[42:45], v[144:147], v[200:203], v[42:45]
	v_mfma_f32_16x16x32_bf16 v[46:49], v[144:147], v[204:207], v[46:49]
	v_mfma_f32_16x16x32_bf16 v[50:53], v[148:151], v[188:191], v[50:53]
	v_mfma_f32_16x16x32_bf16 v[54:57], v[148:151], v[196:199], v[54:57]
	v_mfma_f32_16x16x32_bf16 v[58:61], v[148:151], v[200:203], v[58:61]
	v_mfma_f32_16x16x32_bf16 v[62:65], v[148:151], v[204:207], v[62:65]
	s_waitcnt lgkmcnt(0)
	v_mfma_f32_16x16x32_bf16 v[2:5], v[172:175], v[212:215], v[2:5]
	v_mfma_f32_16x16x32_bf16 v[6:9], v[172:175], v[216:219], v[6:9]
	v_mfma_f32_16x16x32_bf16 v[10:13], v[172:175], v[220:223], v[10:13]
	v_mfma_f32_16x16x32_bf16 v[14:17], v[172:175], v[224:227], v[14:17]
	v_mfma_f32_16x16x32_bf16 v[18:21], v[176:179], v[212:215], v[18:21]
	v_mfma_f32_16x16x32_bf16 v[22:25], v[176:179], v[216:219], v[22:25]
	v_mfma_f32_16x16x32_bf16 v[26:29], v[176:179], v[220:223], v[26:29]
	v_mfma_f32_16x16x32_bf16 v[30:33], v[176:179], v[224:227], v[30:33]
	v_mfma_f32_16x16x32_bf16 v[34:37], v[180:183], v[212:215], v[34:37]
	v_mfma_f32_16x16x32_bf16 v[38:41], v[180:183], v[216:219], v[38:41]
	v_mfma_f32_16x16x32_bf16 v[42:45], v[180:183], v[220:223], v[42:45]
	v_mfma_f32_16x16x32_bf16 v[46:49], v[180:183], v[224:227], v[46:49]
	v_mfma_f32_16x16x32_bf16 v[50:53], v[184:187], v[212:215], v[50:53]
	v_mfma_f32_16x16x32_bf16 v[54:57], v[184:187], v[216:219], v[54:57]
	v_mfma_f32_16x16x32_bf16 v[58:61], v[184:187], v[220:223], v[58:61]
	v_mfma_f32_16x16x32_bf16 v[62:65], v[184:187], v[224:227], v[62:65]
	s_setprio 0
	s_waitcnt vmcnt(6)
	s_barrier
	v_add_u32_e32 v236, s42, v232
	v_add_u32_e32 v237, s42, v233
	ds_read_b128 v[188:191], v236
	ds_read_b128 v[196:199], v236 offset:2048
	ds_read_b128 v[200:203], v236 offset:4096
	ds_read_b128 v[204:207], v236 offset:6144
	ds_read_b128 v[212:215], v237
	ds_read_b128 v[216:219], v237 offset:2048
	ds_read_b128 v[220:223], v237 offset:4096
	ds_read_b128 v[224:227], v237 offset:6144
	s_add_i32 m0, s51, 0x6000
	s_nop 0
	global_load_lds_dwordx4 v229, s[46:47]
	s_add_i32 m0, s51, 0x6400
	s_nop 0
	global_load_lds_dwordx4 v231, s[46:47]
	s_add_i32 m0, s51, 0x8000
	s_nop 0
	global_load_lds_dwordx4 v228, s[48:49]
	s_add_i32 m0, s51, 0x8400
	s_nop 0
	global_load_lds_dwordx4 v230, s[48:49]
	s_add_i32 m0, s51, 0xa000
	s_nop 0
	global_load_lds_dwordx4 v229, s[48:49]
	s_add_i32 m0, s51, 0xa400
	s_nop 0
	global_load_lds_dwordx4 v231, s[48:49]
	s_waitcnt lgkmcnt(4)
	s_setprio 1
	v_mfma_f32_16x16x32_bf16 v[66:69], v[136:139], v[188:191], v[66:69]
	v_mfma_f32_16x16x32_bf16 v[70:73], v[136:139], v[196:199], v[70:73]
	v_mfma_f32_16x16x32_bf16 v[74:77], v[136:139], v[200:203], v[74:77]
	v_mfma_f32_16x16x32_bf16 v[78:81], v[136:139], v[204:207], v[78:81]
	v_mfma_f32_16x16x32_bf16 v[82:85], v[140:143], v[188:191], v[82:85]
	v_mfma_f32_16x16x32_bf16 v[86:89], v[140:143], v[196:199], v[86:89]
	v_mfma_f32_16x16x32_bf16 v[90:93], v[140:143], v[200:203], v[90:93]
	v_mfma_f32_16x16x32_bf16 v[94:97], v[140:143], v[204:207], v[94:97]
	v_mfma_f32_16x16x32_bf16 v[98:101], v[144:147], v[188:191], v[98:101]
	v_mfma_f32_16x16x32_bf16 v[102:105], v[144:147], v[196:199], v[102:105]
	v_mfma_f32_16x16x32_bf16 v[106:109], v[144:147], v[200:203], v[106:109]
	v_mfma_f32_16x16x32_bf16 v[110:113], v[144:147], v[204:207], v[110:113]
	v_mfma_f32_16x16x32_bf16 v[114:117], v[148:151], v[188:191], v[114:117]
	v_mfma_f32_16x16x32_bf16 v[118:121], v[148:151], v[196:199], v[118:121]
	v_mfma_f32_16x16x32_bf16 v[122:125], v[148:151], v[200:203], v[122:125]
	v_mfma_f32_16x16x32_bf16 v[126:129], v[148:151], v[204:207], v[126:129]
	s_waitcnt lgkmcnt(0)
	v_mfma_f32_16x16x32_bf16 v[66:69], v[172:175], v[212:215], v[66:69]
	v_mfma_f32_16x16x32_bf16 v[70:73], v[172:175], v[216:219], v[70:73]
	v_mfma_f32_16x16x32_bf16 v[74:77], v[172:175], v[220:223], v[74:77]
	v_mfma_f32_16x16x32_bf16 v[78:81], v[172:175], v[224:227], v[78:81]
	v_mfma_f32_16x16x32_bf16 v[82:85], v[176:179], v[212:215], v[82:85]
	v_mfma_f32_16x16x32_bf16 v[86:89], v[176:179], v[216:219], v[86:89]
	v_mfma_f32_16x16x32_bf16 v[90:93], v[176:179], v[220:223], v[90:93]
	v_mfma_f32_16x16x32_bf16 v[94:97], v[176:179], v[224:227], v[94:97]
	v_mfma_f32_16x16x32_bf16 v[98:101], v[180:183], v[212:215], v[98:101]
	v_mfma_f32_16x16x32_bf16 v[102:105], v[180:183], v[216:219], v[102:105]
	v_mfma_f32_16x16x32_bf16 v[106:109], v[180:183], v[220:223], v[106:109]
	v_mfma_f32_16x16x32_bf16 v[110:113], v[180:183], v[224:227], v[110:113]
	v_mfma_f32_16x16x32_bf16 v[114:117], v[184:187], v[212:215], v[114:117]
	v_mfma_f32_16x16x32_bf16 v[118:121], v[184:187], v[216:219], v[118:121]
	v_mfma_f32_16x16x32_bf16 v[122:125], v[184:187], v[220:223], v[122:125]
	v_mfma_f32_16x16x32_bf16 v[126:129], v[184:187], v[224:227], v[126:129]
	s_setprio 0
	v_add_u32_e32 v228, 0x80, v228
	v_add_u32_e32 v229, 0x80, v229
	v_add_u32_e32 v230, 0x80, v230
	v_add_u32_e32 v231, 0x80, v231
	s_waitcnt vmcnt(4)
	s_barrier
	s_add_i32 s52, s52, 1
	s_cmp_lt_u32 s52, 10
	s_cbranch_scc1 .Lgu2_loop
	v_add_u32_e32 v234, s22, v232
	v_add_u32_e32 v236, s28, v232
	v_add_u32_e32 v235, s22, v233
	v_add_u32_e32 v237, s28, v233
	ds_read_b128 v[136:139], v234
	ds_read_b128 v[140:143], v234 offset:2048
	ds_read_b128 v[144:147], v234 offset:4096
	ds_read_b128 v[148:151], v234 offset:6144
	ds_read_b128 v[188:191], v236
	ds_read_b128 v[196:199], v236 offset:2048
	ds_read_b128 v[200:203], v236 offset:4096
	ds_read_b128 v[204:207], v236 offset:6144
	ds_read_b128 v[172:175], v235
	ds_read_b128 v[176:179], v235 offset:2048
	ds_read_b128 v[180:183], v235 offset:4096
	ds_read_b128 v[184:187], v235 offset:6144
	ds_read_b128 v[212:215], v237
	ds_read_b128 v[216:219], v237 offset:2048
	ds_read_b128 v[220:223], v237 offset:4096
	ds_read_b128 v[224:227], v237 offset:6144
	s_add_i32 m0, s51, 0xc000
	s_nop 0
	global_load_lds_dwordx4 v228, s[44:45]
	s_add_i32 m0, s51, 0xc400
	s_nop 0
	global_load_lds_dwordx4 v230, s[44:45]
	s_add_i32 m0, s51, 0xe000
	s_nop 0
	global_load_lds_dwordx4 v229, s[44:45]
	s_add_i32 m0, s51, 0xe400
	s_nop 0
	global_load_lds_dwordx4 v231, s[44:45]
	s_add_i32 m0, s51, 0x10000
	s_nop 0
	global_load_lds_dwordx4 v228, s[46:47]
	s_add_i32 m0, s51, 0x10400
	s_nop 0
	global_load_lds_dwordx4 v230, s[46:47]
	s_waitcnt lgkmcnt(8)
	s_setprio 1
	v_mfma_f32_16x16x32_bf16 v[2:5], v[136:139], v[188:191], v[2:5]
	v_mfma_f32_16x16x32_bf16 v[6:9], v[136:139], v[196:199], v[6:9]
	v_mfma_f32_16x16x32_bf16 v[10:13], v[136:139], v[200:203], v[10:13]
	v_mfma_f32_16x16x32_bf16 v[14:17], v[136:139], v[204:207], v[14:17]
	v_mfma_f32_16x16x32_bf16 v[18:21], v[140:143], v[188:191], v[18:21]
	v_mfma_f32_16x16x32_bf16 v[22:25], v[140:143], v[196:199], v[22:25]
	v_mfma_f32_16x16x32_bf16 v[26:29], v[140:143], v[200:203], v[26:29]
	v_mfma_f32_16x16x32_bf16 v[30:33], v[140:143], v[204:207], v[30:33]
	v_mfma_f32_16x16x32_bf16 v[34:37], v[144:147], v[188:191], v[34:37]
	v_mfma_f32_16x16x32_bf16 v[38:41], v[144:147], v[196:199], v[38:41]
	v_mfma_f32_16x16x32_bf16 v[42:45], v[144:147], v[200:203], v[42:45]
	v_mfma_f32_16x16x32_bf16 v[46:49], v[144:147], v[204:207], v[46:49]
	v_mfma_f32_16x16x32_bf16 v[50:53], v[148:151], v[188:191], v[50:53]
	v_mfma_f32_16x16x32_bf16 v[54:57], v[148:151], v[196:199], v[54:57]
	v_mfma_f32_16x16x32_bf16 v[58:61], v[148:151], v[200:203], v[58:61]
	v_mfma_f32_16x16x32_bf16 v[62:65], v[148:151], v[204:207], v[62:65]
	s_waitcnt lgkmcnt(0)
	v_mfma_f32_16x16x32_bf16 v[2:5], v[172:175], v[212:215], v[2:5]
	v_mfma_f32_16x16x32_bf16 v[6:9], v[172:175], v[216:219], v[6:9]
	v_mfma_f32_16x16x32_bf16 v[10:13], v[172:175], v[220:223], v[10:13]
	v_mfma_f32_16x16x32_bf16 v[14:17], v[172:175], v[224:227], v[14:17]
	v_mfma_f32_16x16x32_bf16 v[18:21], v[176:179], v[212:215], v[18:21]
	v_mfma_f32_16x16x32_bf16 v[22:25], v[176:179], v[216:219], v[22:25]
	v_mfma_f32_16x16x32_bf16 v[26:29], v[176:179], v[220:223], v[26:29]
	v_mfma_f32_16x16x32_bf16 v[30:33], v[176:179], v[224:227], v[30:33]
	v_mfma_f32_16x16x32_bf16 v[34:37], v[180:183], v[212:215], v[34:37]
	v_mfma_f32_16x16x32_bf16 v[38:41], v[180:183], v[216:219], v[38:41]
	v_mfma_f32_16x16x32_bf16 v[42:45], v[180:183], v[220:223], v[42:45]
	v_mfma_f32_16x16x32_bf16 v[46:49], v[180:183], v[224:227], v[46:49]
	v_mfma_f32_16x16x32_bf16 v[50:53], v[184:187], v[212:215], v[50:53]
	v_mfma_f32_16x16x32_bf16 v[54:57], v[184:187], v[216:219], v[54:57]
	v_mfma_f32_16x16x32_bf16 v[58:61], v[184:187], v[220:223], v[58:61]
	v_mfma_f32_16x16x32_bf16 v[62:65], v[184:187], v[224:227], v[62:65]
	s_setprio 0
	s_waitcnt vmcnt(6)
	s_barrier
	v_add_u32_e32 v236, s40, v232
	v_add_u32_e32 v237, s40, v233
	ds_read_b128 v[188:191], v236
	ds_read_b128 v[196:199], v236 offset:2048
	ds_read_b128 v[200:203], v236 offset:4096
	ds_read_b128 v[204:207], v236 offset:6144
	ds_read_b128 v[212:215], v237
	ds_read_b128 v[216:219], v237 offset:2048
	ds_read_b128 v[220:223], v237 offset:4096
	ds_read_b128 v[224:227], v237 offset:6144
	s_mov_b32 m0, s51
	s_nop 0
	global_load_lds_dwordx4 v229, s[46:47]
	s_add_i32 m0, s51, 0x400
	s_nop 0
	global_load_lds_dwordx4 v231, s[46:47]
	s_add_i32 m0, s51, 0x2000
	s_nop 0
	global_load_lds_dwordx4 v228, s[48:49]
	s_add_i32 m0, s51, 0x2400
	s_nop 0
	global_load_lds_dwordx4 v230, s[48:49]
	s_add_i32 m0, s51, 0x4000
	s_nop 0
	global_load_lds_dwordx4 v229, s[48:49]
	s_add_i32 m0, s51, 0x4400
	s_nop 0
	global_load_lds_dwordx4 v231, s[48:49]
	s_waitcnt lgkmcnt(4)
	s_setprio 1
	v_mfma_f32_16x16x32_bf16 v[66:69], v[136:139], v[188:191], v[66:69]
	v_mfma_f32_16x16x32_bf16 v[70:73], v[136:139], v[196:199], v[70:73]
	v_mfma_f32_16x16x32_bf16 v[74:77], v[136:139], v[200:203], v[74:77]
	v_mfma_f32_16x16x32_bf16 v[78:81], v[136:139], v[204:207], v[78:81]
	v_mfma_f32_16x16x32_bf16 v[82:85], v[140:143], v[188:191], v[82:85]
	v_mfma_f32_16x16x32_bf16 v[86:89], v[140:143], v[196:199], v[86:89]
	v_mfma_f32_16x16x32_bf16 v[90:93], v[140:143], v[200:203], v[90:93]
	v_mfma_f32_16x16x32_bf16 v[94:97], v[140:143], v[204:207], v[94:97]
	v_mfma_f32_16x16x32_bf16 v[98:101], v[144:147], v[188:191], v[98:101]
	v_mfma_f32_16x16x32_bf16 v[102:105], v[144:147], v[196:199], v[102:105]
	v_mfma_f32_16x16x32_bf16 v[106:109], v[144:147], v[200:203], v[106:109]
	v_mfma_f32_16x16x32_bf16 v[110:113], v[144:147], v[204:207], v[110:113]
	v_mfma_f32_16x16x32_bf16 v[114:117], v[148:151], v[188:191], v[114:117]
	v_mfma_f32_16x16x32_bf16 v[118:121], v[148:151], v[196:199], v[118:121]
	v_mfma_f32_16x16x32_bf16 v[122:125], v[148:151], v[200:203], v[122:125]
	v_mfma_f32_16x16x32_bf16 v[126:129], v[148:151], v[204:207], v[126:129]
	s_waitcnt lgkmcnt(0)
	v_mfma_f32_16x16x32_bf16 v[66:69], v[172:175], v[212:215], v[66:69]
	v_mfma_f32_16x16x32_bf16 v[70:73], v[172:175], v[216:219], v[70:73]
	v_mfma_f32_16x16x32_bf16 v[74:77], v[172:175], v[220:223], v[74:77]
	v_mfma_f32_16x16x32_bf16 v[78:81], v[172:175], v[224:227], v[78:81]
	v_mfma_f32_16x16x32_bf16 v[82:85], v[176:179], v[212:215], v[82:85]
	v_mfma_f32_16x16x32_bf16 v[86:89], v[176:179], v[216:219], v[86:89]
	v_mfma_f32_16x16x32_bf16 v[90:93], v[176:179], v[220:223], v[90:93]
	v_mfma_f32_16x16x32_bf16 v[94:97], v[176:179], v[224:227], v[94:97]
	v_mfma_f32_16x16x32_bf16 v[98:101], v[180:183], v[212:215], v[98:101]
	v_mfma_f32_16x16x32_bf16 v[102:105], v[180:183], v[216:219], v[102:105]
	v_mfma_f32_16x16x32_bf16 v[106:109], v[180:183], v[220:223], v[106:109]
	v_mfma_f32_16x16x32_bf16 v[110:113], v[180:183], v[224:227], v[110:113]
	v_mfma_f32_16x16x32_bf16 v[114:117], v[184:187], v[212:215], v[114:117]
	v_mfma_f32_16x16x32_bf16 v[118:121], v[184:187], v[216:219], v[118:121]
	v_mfma_f32_16x16x32_bf16 v[122:125], v[184:187], v[220:223], v[122:125]
	v_mfma_f32_16x16x32_bf16 v[126:129], v[184:187], v[224:227], v[126:129]
	s_setprio 0
	v_add_u32_e32 v228, 0x80, v228
	v_add_u32_e32 v229, 0x80, v229
	v_add_u32_e32 v230, 0x80, v230
	v_add_u32_e32 v231, 0x80, v231
	s_waitcnt vmcnt(4)
	s_barrier
	v_add_u32_e32 v234, s23, v232
	v_add_u32_e32 v236, s29, v232
	v_add_u32_e32 v235, s23, v233
	v_add_u32_e32 v237, s29, v233
	ds_read_b128 v[136:139], v234
	ds_read_b128 v[140:143], v234 offset:2048
	ds_read_b128 v[144:147], v234 offset:4096
	ds_read_b128 v[148:151], v234 offset:6144
	ds_read_b128 v[188:191], v236
	ds_read_b128 v[196:199], v236 offset:2048
	ds_read_b128 v[200:203], v236 offset:4096
	ds_read_b128 v[204:207], v236 offset:6144
	ds_read_b128 v[172:175], v235
	ds_read_b128 v[176:179], v235 offset:2048
	ds_read_b128 v[180:183], v235 offset:4096
	ds_read_b128 v[184:187], v235 offset:6144
	ds_read_b128 v[212:215], v237
	ds_read_b128 v[216:219], v237 offset:2048
	ds_read_b128 v[220:223], v237 offset:4096
	ds_read_b128 v[224:227], v237 offset:6144
	s_waitcnt lgkmcnt(8)
	s_setprio 1
	v_mfma_f32_16x16x32_bf16 v[2:5], v[136:139], v[188:191], v[2:5]
	v_mfma_f32_16x16x32_bf16 v[6:9], v[136:139], v[196:199], v[6:9]
	v_mfma_f32_16x16x32_bf16 v[10:13], v[136:139], v[200:203], v[10:13]
	v_mfma_f32_16x16x32_bf16 v[14:17], v[136:139], v[204:207], v[14:17]
	v_mfma_f32_16x16x32_bf16 v[18:21], v[140:143], v[188:191], v[18:21]
	v_mfma_f32_16x16x32_bf16 v[22:25], v[140:143], v[196:199], v[22:25]
	v_mfma_f32_16x16x32_bf16 v[26:29], v[140:143], v[200:203], v[26:29]
	v_mfma_f32_16x16x32_bf16 v[30:33], v[140:143], v[204:207], v[30:33]
	v_mfma_f32_16x16x32_bf16 v[34:37], v[144:147], v[188:191], v[34:37]
	v_mfma_f32_16x16x32_bf16 v[38:41], v[144:147], v[196:199], v[38:41]
	v_mfma_f32_16x16x32_bf16 v[42:45], v[144:147], v[200:203], v[42:45]
	v_mfma_f32_16x16x32_bf16 v[46:49], v[144:147], v[204:207], v[46:49]
	v_mfma_f32_16x16x32_bf16 v[50:53], v[148:151], v[188:191], v[50:53]
	v_mfma_f32_16x16x32_bf16 v[54:57], v[148:151], v[196:199], v[54:57]
	v_mfma_f32_16x16x32_bf16 v[58:61], v[148:151], v[200:203], v[58:61]
	v_mfma_f32_16x16x32_bf16 v[62:65], v[148:151], v[204:207], v[62:65]
	s_waitcnt lgkmcnt(0)
	v_mfma_f32_16x16x32_bf16 v[2:5], v[172:175], v[212:215], v[2:5]
	v_mfma_f32_16x16x32_bf16 v[6:9], v[172:175], v[216:219], v[6:9]
	v_mfma_f32_16x16x32_bf16 v[10:13], v[172:175], v[220:223], v[10:13]
	v_mfma_f32_16x16x32_bf16 v[14:17], v[172:175], v[224:227], v[14:17]
	v_mfma_f32_16x16x32_bf16 v[18:21], v[176:179], v[212:215], v[18:21]
	v_mfma_f32_16x16x32_bf16 v[22:25], v[176:179], v[216:219], v[22:25]
	v_mfma_f32_16x16x32_bf16 v[26:29], v[176:179], v[220:223], v[26:29]
	v_mfma_f32_16x16x32_bf16 v[30:33], v[176:179], v[224:227], v[30:33]
	v_mfma_f32_16x16x32_bf16 v[34:37], v[180:183], v[212:215], v[34:37]
	v_mfma_f32_16x16x32_bf16 v[38:41], v[180:183], v[216:219], v[38:41]
	v_mfma_f32_16x16x32_bf16 v[42:45], v[180:183], v[220:223], v[42:45]
	v_mfma_f32_16x16x32_bf16 v[46:49], v[180:183], v[224:227], v[46:49]
	v_mfma_f32_16x16x32_bf16 v[50:53], v[184:187], v[212:215], v[50:53]
	v_mfma_f32_16x16x32_bf16 v[54:57], v[184:187], v[216:219], v[54:57]
	v_mfma_f32_16x16x32_bf16 v[58:61], v[184:187], v[220:223], v[58:61]
	v_mfma_f32_16x16x32_bf16 v[62:65], v[184:187], v[224:227], v[62:65]
	s_setprio 0
	s_waitcnt vmcnt(0)
	s_barrier
	v_add_u32_e32 v236, s41, v232
	v_add_u32_e32 v237, s41, v233
	ds_read_b128 v[188:191], v236
	ds_read_b128 v[196:199], v236 offset:2048
	ds_read_b128 v[200:203], v236 offset:4096
	ds_read_b128 v[204:207], v236 offset:6144
	ds_read_b128 v[212:215], v237
	ds_read_b128 v[216:219], v237 offset:2048
	ds_read_b128 v[220:223], v237 offset:4096
	ds_read_b128 v[224:227], v237 offset:6144
	s_waitcnt lgkmcnt(4)
	s_setprio 1
	v_mfma_f32_16x16x32_bf16 v[66:69], v[136:139], v[188:191], v[66:69]
	v_mfma_f32_16x16x32_bf16 v[70:73], v[136:139], v[196:199], v[70:73]
	v_mfma_f32_16x16x32_bf16 v[74:77], v[136:139], v[200:203], v[74:77]
	v_mfma_f32_16x16x32_bf16 v[78:81], v[136:139], v[204:207], v[78:81]
	v_mfma_f32_16x16x32_bf16 v[82:85], v[140:143], v[188:191], v[82:85]
	v_mfma_f32_16x16x32_bf16 v[86:89], v[140:143], v[196:199], v[86:89]
	v_mfma_f32_16x16x32_bf16 v[90:93], v[140:143], v[200:203], v[90:93]
	v_mfma_f32_16x16x32_bf16 v[94:97], v[140:143], v[204:207], v[94:97]
	v_mfma_f32_16x16x32_bf16 v[98:101], v[144:147], v[188:191], v[98:101]
	v_mfma_f32_16x16x32_bf16 v[102:105], v[144:147], v[196:199], v[102:105]
	v_mfma_f32_16x16x32_bf16 v[106:109], v[144:147], v[200:203], v[106:109]
	v_mfma_f32_16x16x32_bf16 v[110:113], v[144:147], v[204:207], v[110:113]
	v_mfma_f32_16x16x32_bf16 v[114:117], v[148:151], v[188:191], v[114:117]
	v_mfma_f32_16x16x32_bf16 v[118:121], v[148:151], v[196:199], v[118:121]
	v_mfma_f32_16x16x32_bf16 v[122:125], v[148:151], v[200:203], v[122:125]
	v_mfma_f32_16x16x32_bf16 v[126:129], v[148:151], v[204:207], v[126:129]
	s_waitcnt lgkmcnt(0)
	v_mfma_f32_16x16x32_bf16 v[66:69], v[172:175], v[212:215], v[66:69]
	v_mfma_f32_16x16x32_bf16 v[70:73], v[172:175], v[216:219], v[70:73]
	v_mfma_f32_16x16x32_bf16 v[74:77], v[172:175], v[220:223], v[74:77]
	v_mfma_f32_16x16x32_bf16 v[78:81], v[172:175], v[224:227], v[78:81]
	v_mfma_f32_16x16x32_bf16 v[82:85], v[176:179], v[212:215], v[82:85]
	v_mfma_f32_16x16x32_bf16 v[86:89], v[176:179], v[216:219], v[86:89]
	v_mfma_f32_16x16x32_bf16 v[90:93], v[176:179], v[220:223], v[90:93]
	v_mfma_f32_16x16x32_bf16 v[94:97], v[176:179], v[224:227], v[94:97]
	v_mfma_f32_16x16x32_bf16 v[98:101], v[180:183], v[212:215], v[98:101]
	v_mfma_f32_16x16x32_bf16 v[102:105], v[180:183], v[216:219], v[102:105]
	v_mfma_f32_16x16x32_bf16 v[106:109], v[180:183], v[220:223], v[106:109]
	v_mfma_f32_16x16x32_bf16 v[110:113], v[180:183], v[224:227], v[110:113]
	v_mfma_f32_16x16x32_bf16 v[114:117], v[184:187], v[212:215], v[114:117]
	v_mfma_f32_16x16x32_bf16 v[118:121], v[184:187], v[216:219], v[118:121]
	v_mfma_f32_16x16x32_bf16 v[122:125], v[184:187], v[220:223], v[122:125]
	v_mfma_f32_16x16x32_bf16 v[126:129], v[184:187], v[224:227], v[126:129]
	s_setprio 0
	s_nop 7
	s_barrier
	s_mov_b32 s32, s53
	s_mov_b32 s43, s54
	s_add_i32 s55, s55, 1
	s_cmp_lt_u32 s55, 5
	s_cbranch_scc0 .Lgu2_nonext
	s_load_dwordx2 s[44:45], s[12:13], 0x160
	s_load_dwordx2 s[46:47], s[12:13], 0x130
	s_bfe_u32 s53, s21, 0x30006
	s_lshl_b32 s53, s53, 3
	s_and_b32 s56, s21, 7
	s_or_b32 s53, s53, s56
	s_lshl_b32 s53, s53, 7
	s_bfe_u32 s54, s21, 0x30003
	s_lshl_b32 s56, s55, 4
	s_add_i32 s54, s54, s56
	s_lshl_b32 s54, s54, 7
	v_lshrrev_b32_e32 v196, 6, v131
	v_and_b32_e32 v197, 63, v131
	s_nop 0
	v_readfirstlane_b32 s50, v196
	v_lshrrev_b32_e32 v196, 3, v197
	v_lshrrev_b32_e32 v198, 4, v197
	v_and_b32_e32 v199, 7, v197
	s_movk_i32 s56, 0x1080
	v_xor_b32_e32 v200, v199, v198
	v_lshlrev_b32_e32 v200, 4, v200
	v_mad_u32_u24 v228, v196, s56, v200
	v_or_b32_e32 v198, 4, v198
	v_xor_b32_e32 v200, v199, v198
	v_lshlrev_b32_e32 v200, 4, v200
	v_add_u32_e32 v196, 8, v196
	v_mad_u32_u24 v230, v196, s56, v200
	v_add_u32_e32 v229, 0x42000, v228
	v_add_u32_e32 v231, 0x42000, v230
	v_and_b32_e32 v196, 15, v197
	v_lshrrev_b32_e32 v198, 4, v197
	v_bfe_u32 v199, v197, 1, 3
	v_xor_b32_e32 v199, v198, v199
	v_lshlrev_b32_e32 v199, 4, v199
	v_lshl_or_b32 v232, v196, 7, v199
	v_xor_b32_e32 v233, 64, v232
	s_lshr_b32 s56, s50, 1
	s_and_b32 s57, s50, 1
	s_mul_i32 s0, s56, 64*528
	s_lshl_b32 s52, s57, 8
	s_add_i32 s0, s0, s52
	s_add_i32 s0, s0, 16
	v_mul_u32_u24_e32 v198, 4*528, v198
	v_lshl_add_u32 v198, v196, 2, v198
	v_add_u32_e32 v238, s0, v198
	s_add_i32 s22, s56, 0
	s_lshl_b32 s22, s22, 13
	s_add_i32 s22, s22, 16
	s_add_i32 s28, s57, 2
	s_lshl_b32 s28, s28, 13
	s_add_i32 s28, s28, 16
	s_add_i32 s40, s57, 4
	s_lshl_b32 s40, s40, 13
	s_add_i32 s40, s40, 16
	s_add_i32 s23, s56, 6
	s_lshl_b32 s23, s23, 13
	s_add_i32 s23, s23, 16
	s_add_i32 s29, s57, 8
	s_cmp_ge_u32 s29, 9
	s_cselect_b32 s0, 9, 0
	s_sub_i32 s29, s29, s0
	s_lshl_b32 s29, s29, 13
	s_add_i32 s29, s29, 16
	s_add_i32 s41, s57, 1
	s_lshl_b32 s41, s41, 13
	s_add_i32 s41, s41, 16
	s_add_i32 s24, s56, 3
	s_lshl_b32 s24, s24, 13
	s_add_i32 s24, s24, 16
	s_add_i32 s30, s57, 5
	s_lshl_b32 s30, s30, 13
	s_add_i32 s30, s30, 16
	s_add_i32 s42, s57, 7
	s_lshl_b32 s42, s42, 13
	s_add_i32 s42, s42, 16
	s_lshl_b32 s56, s50, 4
	s_add_i32 s57, s53, s56
	s_add_i32 s56, s54, s56
	s_mul_i32 s57, s57, 0x1080
	s_mul_i32 s56, s56, 0x1080
	s_waitcnt lgkmcnt(0)
	s_add_u32 s44, s44, s57
	s_addc_u32 s45, s45, 0
	s_add_u32 s46, s46, s56
	s_addc_u32 s47, s47, 0
	s_add_u32 s48, s46, 0x420000
	s_addc_u32 s49, s47, 0
	s_lshl_b32 s51, s50, 11
	s_add_i32 s51, s51, 16
	s_mov_b32 m0, s51
	s_nop 0
	global_load_lds_dwordx4 v228, s[44:45]
	s_add_i32 m0, s51, 0x400
	s_nop 0
	global_load_lds_dwordx4 v230, s[44:45]
	s_add_i32 m0, s51, 0x2000
	s_nop 0
	global_load_lds_dwordx4 v229, s[44:45]
	s_add_i32 m0, s51, 0x2400
	s_nop 0
	global_load_lds_dwordx4 v231, s[44:45]
	s_add_i32 m0, s51, 0x4000
	s_nop 0
	global_load_lds_dwordx4 v228, s[46:47]
	s_add_i32 m0, s51, 0x4400
	s_nop 0
	global_load_lds_dwordx4 v230, s[46:47]
	s_add_i32 m0, s51, 0x6000
	s_nop 0
	global_load_lds_dwordx4 v229, s[46:47]
	s_add_i32 m0, s51, 0x6400
	s_nop 0
	global_load_lds_dwordx4 v231, s[46:47]
	s_add_i32 m0, s51, 0x8000
	s_nop 0
	global_load_lds_dwordx4 v228, s[48:49]
	s_add_i32 m0, s51, 0x8400
	s_nop 0
	global_load_lds_dwordx4 v230, s[48:49]
	s_add_i32 m0, s51, 0xa000
	s_nop 0
	global_load_lds_dwordx4 v229, s[48:49]
	s_add_i32 m0, s51, 0xa400
	s_nop 0
	global_load_lds_dwordx4 v231, s[48:49]
	v_add_u32_e32 v228, 0x80, v228
	v_add_u32_e32 v229, 0x80, v229
	v_add_u32_e32 v230, 0x80, v230
	v_add_u32_e32 v231, 0x80, v231
.Lgu2_nonext:
	s_load_dwordx2 s[58:59], s[12:13], 0x180
	v_mov_b32_e32 v241, 0x3a000000
	v_mov_b32_e32 v242, 0x358637bd
	v_fma_f32 v152, v152, v241, v242
	v_fma_f32 v153, v153, v241, v242
	v_fma_f32 v154, v154, v241, v242
	v_fma_f32 v155, v155, v241, v242
	v_fma_f32 v244, v244, v241, v242
	v_fma_f32 v245, v245, v241, v242
	v_fma_f32 v246, v246, v241, v242
	v_fma_f32 v247, v247, v241, v242
	v_fma_f32 v248, v248, v241, v242
	v_fma_f32 v249, v249, v241, v242
	v_fma_f32 v250, v250, v241, v242
	v_fma_f32 v251, v251, v241, v242
	v_fma_f32 v252, v252, v241, v242
	v_fma_f32 v253, v253, v241, v242
	v_fma_f32 v254, v254, v241, v242
	v_fma_f32 v255, v255, v241, v242
	v_rsq_f32_e32 v152, v152
	v_rsq_f32_e32 v153, v153
	v_rsq_f32_e32 v154, v154
	v_rsq_f32_e32 v155, v155
	v_rsq_f32_e32 v244, v244
	v_rsq_f32_e32 v245, v245
	v_rsq_f32_e32 v246, v246
	v_rsq_f32_e32 v247, v247
	v_rsq_f32_e32 v248, v248
	v_rsq_f32_e32 v249, v249
	v_rsq_f32_e32 v250, v250
	v_rsq_f32_e32 v251, v251
	v_rsq_f32_e32 v252, v252
	v_rsq_f32_e32 v253, v253
	v_rsq_f32_e32 v254, v254
	v_rsq_f32_e32 v255, v255
	v_and_b32_e32 v241, 63, v131
	v_lshrrev_b32_e32 v242, 4, v241
	v_and_b32_e32 v241, 15, v241
	s_lshr_b32 s56, s50, 1
	s_and_b32 s57, s50, 1
	s_mul_i32 s56, s56, 64*144
	s_lshl_b32 s57, s57, 6
	s_add_i32 s56, s56, s57
	s_add_i32 s56, s56, 49168
	v_mul_u32_u24_e32 v242, 4*144, v242
	v_lshl_add_u32 v242, v241, 1, v242
	v_add_u32_e32 v188, s56, v242
	v_lshrrev_b32_e32 v241, 3, v131
	v_and_b32_e32 v242, 7, v131
	v_lshlrev_b32_e32 v242, 4, v242
	v_mul_u32_u24_e32 v189, 144, v241
	s_mov_b32 s57, 0xc010
	v_add3_u32 v189, v189, v242, s57
	s_movk_i32 s56, 0x2c80
	v_mad_u32_u24 v243, v241, s56, v242
	s_mul_i32 s56, s32, 0x2c80
	s_add_i32 s56, s56, s43
	s_waitcnt lgkmcnt(0)
	s_add_u32 s58, s58, s56
	s_addc_u32 s59, s59, 0
	v_mul_f32_e32 v2, v2, v152
	v_mul_f32_e32 v6, v6, v152
	v_mul_f32_e32 v10, v10, v152
	v_mul_f32_e32 v14, v14, v152
	v_mul_f32_e32 v136, 0xbfb8aa3b, v2
	v_mul_f32_e32 v137, 0xbfb8aa3b, v6
	v_exp_f32_e32 v136, v136
	v_exp_f32_e32 v137, v137
	v_mul_f32_e32 v10, v10, v2
	v_mul_f32_e32 v14, v14, v6
	v_add_f32_e32 v136, 1.0, v136
	v_add_f32_e32 v137, 1.0, v137
	v_rcp_f32_e32 v136, v136
	v_rcp_f32_e32 v137, v137
	s_nop 0
	v_mul_f32_e32 v10, v10, v136
	v_mul_f32_e32 v14, v14, v137
	v_cvt_pk_bf16_f32 v10, v10, v14
	ds_write_b16 v188, v10
	ds_write_b16_d16_hi v188, v10 offset:32
	v_mul_f32_e32 v3, v3, v153
	v_mul_f32_e32 v7, v7, v153
	v_mul_f32_e32 v11, v11, v153
	v_mul_f32_e32 v15, v15, v153
	v_mul_f32_e32 v136, 0xbfb8aa3b, v3
	v_mul_f32_e32 v137, 0xbfb8aa3b, v7
	v_exp_f32_e32 v136, v136
	v_exp_f32_e32 v137, v137
	v_mul_f32_e32 v11, v11, v3
	v_mul_f32_e32 v15, v15, v7
	v_add_f32_e32 v136, 1.0, v136
	v_add_f32_e32 v137, 1.0, v137
	v_rcp_f32_e32 v136, v136
	v_rcp_f32_e32 v137, v137
	s_nop 0
	v_mul_f32_e32 v11, v11, v136
	v_mul_f32_e32 v15, v15, v137
	v_cvt_pk_bf16_f32 v11, v11, v15
	ds_write_b16 v188, v11 offset:144
	ds_write_b16_d16_hi v188, v11 offset:176
	v_mul_f32_e32 v4, v4, v154
	v_mul_f32_e32 v8, v8, v154
	v_mul_f32_e32 v12, v12, v154
	v_mul_f32_e32 v16, v16, v154
	v_mul_f32_e32 v136, 0xbfb8aa3b, v4
	v_mul_f32_e32 v137, 0xbfb8aa3b, v8
	v_exp_f32_e32 v136, v136
	v_exp_f32_e32 v137, v137
	v_mul_f32_e32 v12, v12, v4
	v_mul_f32_e32 v16, v16, v8
	v_add_f32_e32 v136, 1.0, v136
	v_add_f32_e32 v137, 1.0, v137
	v_rcp_f32_e32 v136, v136
	v_rcp_f32_e32 v137, v137
	s_nop 0
	v_mul_f32_e32 v12, v12, v136
	v_mul_f32_e32 v16, v16, v137
	v_cvt_pk_bf16_f32 v12, v12, v16
	ds_write_b16 v188, v12 offset:288
	ds_write_b16_d16_hi v188, v12 offset:320
	v_mul_f32_e32 v5, v5, v155
	v_mul_f32_e32 v9, v9, v155
	v_mul_f32_e32 v13, v13, v155
	v_mul_f32_e32 v17, v17, v155
	v_mul_f32_e32 v136, 0xbfb8aa3b, v5
	v_mul_f32_e32 v137, 0xbfb8aa3b, v9
	v_exp_f32_e32 v136, v136
	v_exp_f32_e32 v137, v137
	v_mul_f32_e32 v13, v13, v5
	v_mul_f32_e32 v17, v17, v9
	v_add_f32_e32 v136, 1.0, v136
	v_add_f32_e32 v137, 1.0, v137
	v_rcp_f32_e32 v136, v136
	v_rcp_f32_e32 v137, v137
	s_nop 0
	v_mul_f32_e32 v13, v13, v136
	v_mul_f32_e32 v17, v17, v137
	v_cvt_pk_bf16_f32 v13, v13, v17
	ds_write_b16 v188, v13 offset:432
	ds_write_b16_d16_hi v188, v13 offset:464
	v_mul_f32_e32 v18, v18, v244
	v_mul_f32_e32 v22, v22, v244
	v_mul_f32_e32 v26, v26, v244
	v_mul_f32_e32 v30, v30, v244
	v_mul_f32_e32 v136, 0xbfb8aa3b, v18
	v_mul_f32_e32 v137, 0xbfb8aa3b, v22
	v_exp_f32_e32 v136, v136
	v_exp_f32_e32 v137, v137
	v_mul_f32_e32 v26, v26, v18
	v_mul_f32_e32 v30, v30, v22
	v_add_f32_e32 v136, 1.0, v136
	v_add_f32_e32 v137, 1.0, v137
	v_rcp_f32_e32 v136, v136
	v_rcp_f32_e32 v137, v137
	s_nop 0
	v_mul_f32_e32 v26, v26, v136
	v_mul_f32_e32 v30, v30, v137
	v_cvt_pk_bf16_f32 v26, v26, v30
	ds_write_b16 v188, v26 offset:2304
	ds_write_b16_d16_hi v188, v26 offset:2336
	v_mul_f32_e32 v19, v19, v245
	v_mul_f32_e32 v23, v23, v245
	v_mul_f32_e32 v27, v27, v245
	v_mul_f32_e32 v31, v31, v245
	v_mul_f32_e32 v136, 0xbfb8aa3b, v19
	v_mul_f32_e32 v137, 0xbfb8aa3b, v23
	v_exp_f32_e32 v136, v136
	v_exp_f32_e32 v137, v137
	v_mul_f32_e32 v27, v27, v19
	v_mul_f32_e32 v31, v31, v23
	v_add_f32_e32 v136, 1.0, v136
	v_add_f32_e32 v137, 1.0, v137
	v_rcp_f32_e32 v136, v136
	v_rcp_f32_e32 v137, v137
	s_nop 0
	v_mul_f32_e32 v27, v27, v136
	v_mul_f32_e32 v31, v31, v137
	v_cvt_pk_bf16_f32 v27, v27, v31
	ds_write_b16 v188, v27 offset:2448
	ds_write_b16_d16_hi v188, v27 offset:2480
	v_mul_f32_e32 v20, v20, v246
	v_mul_f32_e32 v24, v24, v246
	v_mul_f32_e32 v28, v28, v246
	v_mul_f32_e32 v32, v32, v246
	v_mul_f32_e32 v136, 0xbfb8aa3b, v20
	v_mul_f32_e32 v137, 0xbfb8aa3b, v24
	v_exp_f32_e32 v136, v136
	v_exp_f32_e32 v137, v137
	v_mul_f32_e32 v28, v28, v20
	v_mul_f32_e32 v32, v32, v24
	v_add_f32_e32 v136, 1.0, v136
	v_add_f32_e32 v137, 1.0, v137
	v_rcp_f32_e32 v136, v136
	v_rcp_f32_e32 v137, v137
	s_nop 0
	v_mul_f32_e32 v28, v28, v136
	v_mul_f32_e32 v32, v32, v137
	v_cvt_pk_bf16_f32 v28, v28, v32
	ds_write_b16 v188, v28 offset:2592
	ds_write_b16_d16_hi v188, v28 offset:2624
	v_mul_f32_e32 v21, v21, v247
	v_mul_f32_e32 v25, v25, v247
	v_mul_f32_e32 v29, v29, v247
	v_mul_f32_e32 v33, v33, v247
	v_mul_f32_e32 v136, 0xbfb8aa3b, v21
	v_mul_f32_e32 v137, 0xbfb8aa3b, v25
	v_exp_f32_e32 v136, v136
	v_exp_f32_e32 v137, v137
	v_mul_f32_e32 v29, v29, v21
	v_mul_f32_e32 v33, v33, v25
	v_add_f32_e32 v136, 1.0, v136
	v_add_f32_e32 v137, 1.0, v137
	v_rcp_f32_e32 v136, v136
	v_rcp_f32_e32 v137, v137
	s_nop 0
	v_mul_f32_e32 v29, v29, v136
	v_mul_f32_e32 v33, v33, v137
	v_cvt_pk_bf16_f32 v29, v29, v33
	ds_write_b16 v188, v29 offset:2736
	ds_write_b16_d16_hi v188, v29 offset:2768
	v_mul_f32_e32 v34, v34, v248
	v_mul_f32_e32 v38, v38, v248
	v_mul_f32_e32 v42, v42, v248
	v_mul_f32_e32 v46, v46, v248
	v_mul_f32_e32 v136, 0xbfb8aa3b, v34
	v_mul_f32_e32 v137, 0xbfb8aa3b, v38
	v_exp_f32_e32 v136, v136
	v_exp_f32_e32 v137, v137
	v_mul_f32_e32 v42, v42, v34
	v_mul_f32_e32 v46, v46, v38
	v_add_f32_e32 v136, 1.0, v136
	v_add_f32_e32 v137, 1.0, v137
	v_rcp_f32_e32 v136, v136
	v_rcp_f32_e32 v137, v137
	s_nop 0
	v_mul_f32_e32 v42, v42, v136
	v_mul_f32_e32 v46, v46, v137
	v_cvt_pk_bf16_f32 v42, v42, v46
	ds_write_b16 v188, v42 offset:4608
	ds_write_b16_d16_hi v188, v42 offset:4640
	v_mul_f32_e32 v35, v35, v249
	v_mul_f32_e32 v39, v39, v249
	v_mul_f32_e32 v43, v43, v249
	v_mul_f32_e32 v47, v47, v249
	v_mul_f32_e32 v136, 0xbfb8aa3b, v35
	v_mul_f32_e32 v137, 0xbfb8aa3b, v39
	v_exp_f32_e32 v136, v136
	v_exp_f32_e32 v137, v137
	v_mul_f32_e32 v43, v43, v35
	v_mul_f32_e32 v47, v47, v39
	v_add_f32_e32 v136, 1.0, v136
	v_add_f32_e32 v137, 1.0, v137
	v_rcp_f32_e32 v136, v136
	v_rcp_f32_e32 v137, v137
	s_nop 0
	v_mul_f32_e32 v43, v43, v136
	v_mul_f32_e32 v47, v47, v137
	v_cvt_pk_bf16_f32 v43, v43, v47
	ds_write_b16 v188, v43 offset:4752
	ds_write_b16_d16_hi v188, v43 offset:4784
	v_mul_f32_e32 v36, v36, v250
	v_mul_f32_e32 v40, v40, v250
	v_mul_f32_e32 v44, v44, v250
	v_mul_f32_e32 v48, v48, v250
	v_mul_f32_e32 v136, 0xbfb8aa3b, v36
	v_mul_f32_e32 v137, 0xbfb8aa3b, v40
	v_exp_f32_e32 v136, v136
	v_exp_f32_e32 v137, v137
	v_mul_f32_e32 v44, v44, v36
	v_mul_f32_e32 v48, v48, v40
	v_add_f32_e32 v136, 1.0, v136
	v_add_f32_e32 v137, 1.0, v137
	v_rcp_f32_e32 v136, v136
	v_rcp_f32_e32 v137, v137
	s_nop 0
	v_mul_f32_e32 v44, v44, v136
	v_mul_f32_e32 v48, v48, v137
	v_cvt_pk_bf16_f32 v44, v44, v48
	ds_write_b16 v188, v44 offset:4896
	ds_write_b16_d16_hi v188, v44 offset:4928
	v_mul_f32_e32 v37, v37, v251
	v_mul_f32_e32 v41, v41, v251
	v_mul_f32_e32 v45, v45, v251
	v_mul_f32_e32 v49, v49, v251
	v_mul_f32_e32 v136, 0xbfb8aa3b, v37
	v_mul_f32_e32 v137, 0xbfb8aa3b, v41
	v_exp_f32_e32 v136, v136
	v_exp_f32_e32 v137, v137
	v_mul_f32_e32 v45, v45, v37
	v_mul_f32_e32 v49, v49, v41
	v_add_f32_e32 v136, 1.0, v136
	v_add_f32_e32 v137, 1.0, v137
	v_rcp_f32_e32 v136, v136
	v_rcp_f32_e32 v137, v137
	s_nop 0
	v_mul_f32_e32 v45, v45, v136
	v_mul_f32_e32 v49, v49, v137
	v_cvt_pk_bf16_f32 v45, v45, v49
	ds_write_b16 v188, v45 offset:5040
	ds_write_b16_d16_hi v188, v45 offset:5072
	v_mul_f32_e32 v50, v50, v252
	v_mul_f32_e32 v54, v54, v252
	v_mul_f32_e32 v58, v58, v252
	v_mul_f32_e32 v62, v62, v252
	v_mul_f32_e32 v136, 0xbfb8aa3b, v50
	v_mul_f32_e32 v137, 0xbfb8aa3b, v54
	v_exp_f32_e32 v136, v136
	v_exp_f32_e32 v137, v137
	v_mul_f32_e32 v58, v58, v50
	v_mul_f32_e32 v62, v62, v54
	v_add_f32_e32 v136, 1.0, v136
	v_add_f32_e32 v137, 1.0, v137
	v_rcp_f32_e32 v136, v136
	v_rcp_f32_e32 v137, v137
	s_nop 0
	v_mul_f32_e32 v58, v58, v136
	v_mul_f32_e32 v62, v62, v137
	v_cvt_pk_bf16_f32 v58, v58, v62
	ds_write_b16 v188, v58 offset:6912
	ds_write_b16_d16_hi v188, v58 offset:6944
	v_mul_f32_e32 v51, v51, v253
	v_mul_f32_e32 v55, v55, v253
	v_mul_f32_e32 v59, v59, v253
	v_mul_f32_e32 v63, v63, v253
	v_mul_f32_e32 v136, 0xbfb8aa3b, v51
	v_mul_f32_e32 v137, 0xbfb8aa3b, v55
	v_exp_f32_e32 v136, v136
	v_exp_f32_e32 v137, v137
	v_mul_f32_e32 v59, v59, v51
	v_mul_f32_e32 v63, v63, v55
	v_add_f32_e32 v136, 1.0, v136
	v_add_f32_e32 v137, 1.0, v137
	v_rcp_f32_e32 v136, v136
	v_rcp_f32_e32 v137, v137
	s_nop 0
	v_mul_f32_e32 v59, v59, v136
	v_mul_f32_e32 v63, v63, v137
	v_cvt_pk_bf16_f32 v59, v59, v63
	ds_write_b16 v188, v59 offset:7056
	ds_write_b16_d16_hi v188, v59 offset:7088
	v_mul_f32_e32 v52, v52, v254
	v_mul_f32_e32 v56, v56, v254
	v_mul_f32_e32 v60, v60, v254
	v_mul_f32_e32 v64, v64, v254
	v_mul_f32_e32 v136, 0xbfb8aa3b, v52
	v_mul_f32_e32 v137, 0xbfb8aa3b, v56
	v_exp_f32_e32 v136, v136
	v_exp_f32_e32 v137, v137
	v_mul_f32_e32 v60, v60, v52
	v_mul_f32_e32 v64, v64, v56
	v_add_f32_e32 v136, 1.0, v136
	v_add_f32_e32 v137, 1.0, v137
	v_rcp_f32_e32 v136, v136
	v_rcp_f32_e32 v137, v137
	s_nop 0
	v_mul_f32_e32 v60, v60, v136
	v_mul_f32_e32 v64, v64, v137
	v_cvt_pk_bf16_f32 v60, v60, v64
	ds_write_b16 v188, v60 offset:7200
	ds_write_b16_d16_hi v188, v60 offset:7232
	v_mul_f32_e32 v53, v53, v255
	v_mul_f32_e32 v57, v57, v255
	v_mul_f32_e32 v61, v61, v255
	v_mul_f32_e32 v65, v65, v255
	v_mul_f32_e32 v136, 0xbfb8aa3b, v53
	v_mul_f32_e32 v137, 0xbfb8aa3b, v57
	v_exp_f32_e32 v136, v136
	v_exp_f32_e32 v137, v137
	v_mul_f32_e32 v61, v61, v53
	v_mul_f32_e32 v65, v65, v57
	v_add_f32_e32 v136, 1.0, v136
	v_add_f32_e32 v137, 1.0, v137
	v_rcp_f32_e32 v136, v136
	v_rcp_f32_e32 v137, v137
	s_nop 0
	v_mul_f32_e32 v61, v61, v136
	v_mul_f32_e32 v65, v65, v137
	v_cvt_pk_bf16_f32 v61, v61, v65
	ds_write_b16 v188, v61 offset:7344
	ds_write_b16_d16_hi v188, v61 offset:7376
	s_waitcnt lgkmcnt(0)
	s_barrier
	ds_read_b128 v[144:147], v189
	ds_read_b128 v[148:151], v189 offset:4608
	ds_read_b128 v[172:175], v189 offset:9216
	ds_read_b128 v[176:179], v189 offset:13824
	s_mov_b32 s56, s58
	s_mov_b32 s57, s59
	s_waitcnt lgkmcnt(3)
	global_store_dwordx4 v243, v[144:147], s[56:57]
	s_add_u32 s56, s56, 0x59000
	s_addc_u32 s57, s57, 0
	s_waitcnt lgkmcnt(2)
	global_store_dwordx4 v243, v[148:151], s[56:57]
	s_add_u32 s56, s56, 0x59000
	s_addc_u32 s57, s57, 0
	s_waitcnt lgkmcnt(1)
	global_store_dwordx4 v243, v[172:175], s[56:57]
	s_add_u32 s56, s56, 0x59000
	s_addc_u32 s57, s57, 0
	s_waitcnt lgkmcnt(0)
	global_store_dwordx4 v243, v[176:179], s[56:57]
	s_add_u32 s58, s58, 0x400
	s_addc_u32 s59, s59, 0
	s_barrier
	v_mul_f32_e32 v66, v66, v152
	v_mul_f32_e32 v70, v70, v152
	v_mul_f32_e32 v74, v74, v152
	v_mul_f32_e32 v78, v78, v152
	v_mul_f32_e32 v136, 0xbfb8aa3b, v66
	v_mul_f32_e32 v137, 0xbfb8aa3b, v70
	v_exp_f32_e32 v136, v136
	v_exp_f32_e32 v137, v137
	v_mul_f32_e32 v74, v74, v66
	v_mul_f32_e32 v78, v78, v70
	v_add_f32_e32 v136, 1.0, v136
	v_add_f32_e32 v137, 1.0, v137
	v_rcp_f32_e32 v136, v136
	v_rcp_f32_e32 v137, v137
	s_nop 0
	v_mul_f32_e32 v74, v74, v136
	v_mul_f32_e32 v78, v78, v137
	v_cvt_pk_bf16_f32 v74, v74, v78
	ds_write_b16 v188, v74
	ds_write_b16_d16_hi v188, v74 offset:32
	v_mul_f32_e32 v67, v67, v153
	v_mul_f32_e32 v71, v71, v153
	v_mul_f32_e32 v75, v75, v153
	v_mul_f32_e32 v79, v79, v153
	v_mul_f32_e32 v136, 0xbfb8aa3b, v67
	v_mul_f32_e32 v137, 0xbfb8aa3b, v71
	v_exp_f32_e32 v136, v136
	v_exp_f32_e32 v137, v137
	v_mul_f32_e32 v75, v75, v67
	v_mul_f32_e32 v79, v79, v71
	v_add_f32_e32 v136, 1.0, v136
	v_add_f32_e32 v137, 1.0, v137
	v_rcp_f32_e32 v136, v136
	v_rcp_f32_e32 v137, v137
	s_nop 0
	v_mul_f32_e32 v75, v75, v136
	v_mul_f32_e32 v79, v79, v137
	v_cvt_pk_bf16_f32 v75, v75, v79
	ds_write_b16 v188, v75 offset:144
	ds_write_b16_d16_hi v188, v75 offset:176
	v_mul_f32_e32 v68, v68, v154
	v_mul_f32_e32 v72, v72, v154
	v_mul_f32_e32 v76, v76, v154
	v_mul_f32_e32 v80, v80, v154
	v_mul_f32_e32 v136, 0xbfb8aa3b, v68
	v_mul_f32_e32 v137, 0xbfb8aa3b, v72
	v_exp_f32_e32 v136, v136
	v_exp_f32_e32 v137, v137
	v_mul_f32_e32 v76, v76, v68
	v_mul_f32_e32 v80, v80, v72
	v_add_f32_e32 v136, 1.0, v136
	v_add_f32_e32 v137, 1.0, v137
	v_rcp_f32_e32 v136, v136
	v_rcp_f32_e32 v137, v137
	s_nop 0
	v_mul_f32_e32 v76, v76, v136
	v_mul_f32_e32 v80, v80, v137
	v_cvt_pk_bf16_f32 v76, v76, v80
	ds_write_b16 v188, v76 offset:288
	ds_write_b16_d16_hi v188, v76 offset:320
	v_mul_f32_e32 v69, v69, v155
	v_mul_f32_e32 v73, v73, v155
	v_mul_f32_e32 v77, v77, v155
	v_mul_f32_e32 v81, v81, v155
	v_mul_f32_e32 v136, 0xbfb8aa3b, v69
	v_mul_f32_e32 v137, 0xbfb8aa3b, v73
	v_exp_f32_e32 v136, v136
	v_exp_f32_e32 v137, v137
	v_mul_f32_e32 v77, v77, v69
	v_mul_f32_e32 v81, v81, v73
	v_add_f32_e32 v136, 1.0, v136
	v_add_f32_e32 v137, 1.0, v137
	v_rcp_f32_e32 v136, v136
	v_rcp_f32_e32 v137, v137
	s_nop 0
	v_mul_f32_e32 v77, v77, v136
	v_mul_f32_e32 v81, v81, v137
	v_cvt_pk_bf16_f32 v77, v77, v81
	ds_write_b16 v188, v77 offset:432
	ds_write_b16_d16_hi v188, v77 offset:464
	v_mul_f32_e32 v82, v82, v244
	v_mul_f32_e32 v86, v86, v244
	v_mul_f32_e32 v90, v90, v244
	v_mul_f32_e32 v94, v94, v244
	v_mul_f32_e32 v136, 0xbfb8aa3b, v82
	v_mul_f32_e32 v137, 0xbfb8aa3b, v86
	v_exp_f32_e32 v136, v136
	v_exp_f32_e32 v137, v137
	v_mul_f32_e32 v90, v90, v82
	v_mul_f32_e32 v94, v94, v86
	v_add_f32_e32 v136, 1.0, v136
	v_add_f32_e32 v137, 1.0, v137
	v_rcp_f32_e32 v136, v136
	v_rcp_f32_e32 v137, v137
	s_nop 0
	v_mul_f32_e32 v90, v90, v136
	v_mul_f32_e32 v94, v94, v137
	v_cvt_pk_bf16_f32 v90, v90, v94
	ds_write_b16 v188, v90 offset:2304
	ds_write_b16_d16_hi v188, v90 offset:2336
	v_mul_f32_e32 v83, v83, v245
	v_mul_f32_e32 v87, v87, v245
	v_mul_f32_e32 v91, v91, v245
	v_mul_f32_e32 v95, v95, v245
	v_mul_f32_e32 v136, 0xbfb8aa3b, v83
	v_mul_f32_e32 v137, 0xbfb8aa3b, v87
	v_exp_f32_e32 v136, v136
	v_exp_f32_e32 v137, v137
	v_mul_f32_e32 v91, v91, v83
	v_mul_f32_e32 v95, v95, v87
	v_add_f32_e32 v136, 1.0, v136
	v_add_f32_e32 v137, 1.0, v137
	v_rcp_f32_e32 v136, v136
	v_rcp_f32_e32 v137, v137
	s_nop 0
	v_mul_f32_e32 v91, v91, v136
	v_mul_f32_e32 v95, v95, v137
	v_cvt_pk_bf16_f32 v91, v91, v95
	ds_write_b16 v188, v91 offset:2448
	ds_write_b16_d16_hi v188, v91 offset:2480
	v_mul_f32_e32 v84, v84, v246
	v_mul_f32_e32 v88, v88, v246
	v_mul_f32_e32 v92, v92, v246
	v_mul_f32_e32 v96, v96, v246
	v_mul_f32_e32 v136, 0xbfb8aa3b, v84
	v_mul_f32_e32 v137, 0xbfb8aa3b, v88
	v_exp_f32_e32 v136, v136
	v_exp_f32_e32 v137, v137
	v_mul_f32_e32 v92, v92, v84
	v_mul_f32_e32 v96, v96, v88
	v_add_f32_e32 v136, 1.0, v136
	v_add_f32_e32 v137, 1.0, v137
	v_rcp_f32_e32 v136, v136
	v_rcp_f32_e32 v137, v137
	s_nop 0
	v_mul_f32_e32 v92, v92, v136
	v_mul_f32_e32 v96, v96, v137
	v_cvt_pk_bf16_f32 v92, v92, v96
	ds_write_b16 v188, v92 offset:2592
	ds_write_b16_d16_hi v188, v92 offset:2624
	v_mul_f32_e32 v85, v85, v247
	v_mul_f32_e32 v89, v89, v247
	v_mul_f32_e32 v93, v93, v247
	v_mul_f32_e32 v97, v97, v247
	v_mul_f32_e32 v136, 0xbfb8aa3b, v85
	v_mul_f32_e32 v137, 0xbfb8aa3b, v89
	v_exp_f32_e32 v136, v136
	v_exp_f32_e32 v137, v137
	v_mul_f32_e32 v93, v93, v85
	v_mul_f32_e32 v97, v97, v89
	v_add_f32_e32 v136, 1.0, v136
	v_add_f32_e32 v137, 1.0, v137
	v_rcp_f32_e32 v136, v136
	v_rcp_f32_e32 v137, v137
	s_nop 0
	v_mul_f32_e32 v93, v93, v136
	v_mul_f32_e32 v97, v97, v137
	v_cvt_pk_bf16_f32 v93, v93, v97
	ds_write_b16 v188, v93 offset:2736
	ds_write_b16_d16_hi v188, v93 offset:2768
	v_mul_f32_e32 v98, v98, v248
	v_mul_f32_e32 v102, v102, v248
	v_mul_f32_e32 v106, v106, v248
	v_mul_f32_e32 v110, v110, v248
	v_mul_f32_e32 v136, 0xbfb8aa3b, v98
	v_mul_f32_e32 v137, 0xbfb8aa3b, v102
	v_exp_f32_e32 v136, v136
	v_exp_f32_e32 v137, v137
	v_mul_f32_e32 v106, v106, v98
	v_mul_f32_e32 v110, v110, v102
	v_add_f32_e32 v136, 1.0, v136
	v_add_f32_e32 v137, 1.0, v137
	v_rcp_f32_e32 v136, v136
	v_rcp_f32_e32 v137, v137
	s_nop 0
	v_mul_f32_e32 v106, v106, v136
	v_mul_f32_e32 v110, v110, v137
	v_cvt_pk_bf16_f32 v106, v106, v110
	ds_write_b16 v188, v106 offset:4608
	ds_write_b16_d16_hi v188, v106 offset:4640
	v_mul_f32_e32 v99, v99, v249
	v_mul_f32_e32 v103, v103, v249
	v_mul_f32_e32 v107, v107, v249
	v_mul_f32_e32 v111, v111, v249
	v_mul_f32_e32 v136, 0xbfb8aa3b, v99
	v_mul_f32_e32 v137, 0xbfb8aa3b, v103
	v_exp_f32_e32 v136, v136
	v_exp_f32_e32 v137, v137
	v_mul_f32_e32 v107, v107, v99
	v_mul_f32_e32 v111, v111, v103
	v_add_f32_e32 v136, 1.0, v136
	v_add_f32_e32 v137, 1.0, v137
	v_rcp_f32_e32 v136, v136
	v_rcp_f32_e32 v137, v137
	s_nop 0
	v_mul_f32_e32 v107, v107, v136
	v_mul_f32_e32 v111, v111, v137
	v_cvt_pk_bf16_f32 v107, v107, v111
	ds_write_b16 v188, v107 offset:4752
	ds_write_b16_d16_hi v188, v107 offset:4784
	v_mul_f32_e32 v100, v100, v250
	v_mul_f32_e32 v104, v104, v250
	v_mul_f32_e32 v108, v108, v250
	v_mul_f32_e32 v112, v112, v250
	v_mul_f32_e32 v136, 0xbfb8aa3b, v100
	v_mul_f32_e32 v137, 0xbfb8aa3b, v104
	v_exp_f32_e32 v136, v136
	v_exp_f32_e32 v137, v137
	v_mul_f32_e32 v108, v108, v100
	v_mul_f32_e32 v112, v112, v104
	v_add_f32_e32 v136, 1.0, v136
	v_add_f32_e32 v137, 1.0, v137
	v_rcp_f32_e32 v136, v136
	v_rcp_f32_e32 v137, v137
	s_nop 0
	v_mul_f32_e32 v108, v108, v136
	v_mul_f32_e32 v112, v112, v137
	v_cvt_pk_bf16_f32 v108, v108, v112
	ds_write_b16 v188, v108 offset:4896
	ds_write_b16_d16_hi v188, v108 offset:4928
	v_mul_f32_e32 v101, v101, v251
	v_mul_f32_e32 v105, v105, v251
	v_mul_f32_e32 v109, v109, v251
	v_mul_f32_e32 v113, v113, v251
	v_mul_f32_e32 v136, 0xbfb8aa3b, v101
	v_mul_f32_e32 v137, 0xbfb8aa3b, v105
	v_exp_f32_e32 v136, v136
	v_exp_f32_e32 v137, v137
	v_mul_f32_e32 v109, v109, v101
	v_mul_f32_e32 v113, v113, v105
	v_add_f32_e32 v136, 1.0, v136
	v_add_f32_e32 v137, 1.0, v137
	v_rcp_f32_e32 v136, v136
	v_rcp_f32_e32 v137, v137
	s_nop 0
	v_mul_f32_e32 v109, v109, v136
	v_mul_f32_e32 v113, v113, v137
	v_cvt_pk_bf16_f32 v109, v109, v113
	ds_write_b16 v188, v109 offset:5040
	ds_write_b16_d16_hi v188, v109 offset:5072
	v_mul_f32_e32 v114, v114, v252
	v_mul_f32_e32 v118, v118, v252
	v_mul_f32_e32 v122, v122, v252
	v_mul_f32_e32 v126, v126, v252
	v_mul_f32_e32 v136, 0xbfb8aa3b, v114
	v_mul_f32_e32 v137, 0xbfb8aa3b, v118
	v_exp_f32_e32 v136, v136
	v_exp_f32_e32 v137, v137
	v_mul_f32_e32 v122, v122, v114
	v_mul_f32_e32 v126, v126, v118
	v_add_f32_e32 v136, 1.0, v136
	v_add_f32_e32 v137, 1.0, v137
	v_rcp_f32_e32 v136, v136
	v_rcp_f32_e32 v137, v137
	s_nop 0
	v_mul_f32_e32 v122, v122, v136
	v_mul_f32_e32 v126, v126, v137
	v_cvt_pk_bf16_f32 v122, v122, v126
	ds_write_b16 v188, v122 offset:6912
	ds_write_b16_d16_hi v188, v122 offset:6944
	v_mul_f32_e32 v115, v115, v253
	v_mul_f32_e32 v119, v119, v253
	v_mul_f32_e32 v123, v123, v253
	v_mul_f32_e32 v127, v127, v253
	v_mul_f32_e32 v136, 0xbfb8aa3b, v115
	v_mul_f32_e32 v137, 0xbfb8aa3b, v119
	v_exp_f32_e32 v136, v136
	v_exp_f32_e32 v137, v137
	v_mul_f32_e32 v123, v123, v115
	v_mul_f32_e32 v127, v127, v119
	v_add_f32_e32 v136, 1.0, v136
	v_add_f32_e32 v137, 1.0, v137
	v_rcp_f32_e32 v136, v136
	v_rcp_f32_e32 v137, v137
	s_nop 0
	v_mul_f32_e32 v123, v123, v136
	v_mul_f32_e32 v127, v127, v137
	v_cvt_pk_bf16_f32 v123, v123, v127
	ds_write_b16 v188, v123 offset:7056
	ds_write_b16_d16_hi v188, v123 offset:7088
	v_mul_f32_e32 v116, v116, v254
	v_mul_f32_e32 v120, v120, v254
	v_mul_f32_e32 v124, v124, v254
	v_mul_f32_e32 v128, v128, v254
	v_mul_f32_e32 v136, 0xbfb8aa3b, v116
	v_mul_f32_e32 v137, 0xbfb8aa3b, v120
	v_exp_f32_e32 v136, v136
	v_exp_f32_e32 v137, v137
	v_mul_f32_e32 v124, v124, v116
	v_mul_f32_e32 v128, v128, v120
	v_add_f32_e32 v136, 1.0, v136
	v_add_f32_e32 v137, 1.0, v137
	v_rcp_f32_e32 v136, v136
	v_rcp_f32_e32 v137, v137
	s_nop 0
	v_mul_f32_e32 v124, v124, v136
	v_mul_f32_e32 v128, v128, v137
	v_cvt_pk_bf16_f32 v124, v124, v128
	ds_write_b16 v188, v124 offset:7200
	ds_write_b16_d16_hi v188, v124 offset:7232
	v_mul_f32_e32 v117, v117, v255
	v_mul_f32_e32 v121, v121, v255
	v_mul_f32_e32 v125, v125, v255
	v_mul_f32_e32 v129, v129, v255
	v_mul_f32_e32 v136, 0xbfb8aa3b, v117
	v_mul_f32_e32 v137, 0xbfb8aa3b, v121
	v_exp_f32_e32 v136, v136
	v_exp_f32_e32 v137, v137
	v_mul_f32_e32 v125, v125, v117
	v_mul_f32_e32 v129, v129, v121
	v_add_f32_e32 v136, 1.0, v136
	v_add_f32_e32 v137, 1.0, v137
	v_rcp_f32_e32 v136, v136
	v_rcp_f32_e32 v137, v137
	s_nop 0
	v_mul_f32_e32 v125, v125, v136
	v_mul_f32_e32 v129, v129, v137
	v_cvt_pk_bf16_f32 v125, v125, v129
	ds_write_b16 v188, v125 offset:7344
	ds_write_b16_d16_hi v188, v125 offset:7376
	s_waitcnt lgkmcnt(0)
	s_barrier
	ds_read_b128 v[144:147], v189
	ds_read_b128 v[148:151], v189 offset:4608
	ds_read_b128 v[172:175], v189 offset:9216
	ds_read_b128 v[176:179], v189 offset:13824
	s_mov_b32 s56, s58
	s_mov_b32 s57, s59
	s_waitcnt lgkmcnt(3)
	global_store_dwordx4 v243, v[144:147], s[56:57]
	s_add_u32 s56, s56, 0x59000
	s_addc_u32 s57, s57, 0
	s_waitcnt lgkmcnt(2)
	global_store_dwordx4 v243, v[148:151], s[56:57]
	s_add_u32 s56, s56, 0x59000
	s_addc_u32 s57, s57, 0
	s_waitcnt lgkmcnt(1)
	global_store_dwordx4 v243, v[172:175], s[56:57]
	s_add_u32 s56, s56, 0x59000
	s_addc_u32 s57, s57, 0
	s_waitcnt lgkmcnt(0)
	global_store_dwordx4 v243, v[176:179], s[56:57]
	s_cmp_lt_u32 s55, 5
	s_barrier
	s_cbranch_scc0 .Lgu2_lastp
	v_mov_b32_e32 v2, 0
	v_mov_b32_e32 v3, 0
	v_mov_b32_e32 v4, 0
	v_mov_b32_e32 v5, 0
	v_mov_b32_e32 v6, 0
	v_mov_b32_e32 v7, 0
	v_mov_b32_e32 v8, 0
	v_mov_b32_e32 v9, 0
	v_mov_b32_e32 v10, 0
	v_mov_b32_e32 v11, 0
	v_mov_b32_e32 v12, 0
	v_mov_b32_e32 v13, 0
	v_mov_b32_e32 v14, 0
	v_mov_b32_e32 v15, 0
	v_mov_b32_e32 v16, 0
	v_mov_b32_e32 v17, 0
	v_mov_b32_e32 v18, 0
	v_mov_b32_e32 v19, 0
	v_mov_b32_e32 v20, 0
	v_mov_b32_e32 v21, 0
	v_mov_b32_e32 v22, 0
	v_mov_b32_e32 v23, 0
	v_mov_b32_e32 v24, 0
	v_mov_b32_e32 v25, 0
	v_mov_b32_e32 v26, 0
	v_mov_b32_e32 v27, 0
	v_mov_b32_e32 v28, 0
	v_mov_b32_e32 v29, 0
	v_mov_b32_e32 v30, 0
	v_mov_b32_e32 v31, 0
	v_mov_b32_e32 v32, 0
	v_mov_b32_e32 v33, 0
	v_mov_b32_e32 v34, 0
	v_mov_b32_e32 v35, 0
	v_mov_b32_e32 v36, 0
	v_mov_b32_e32 v37, 0
	v_mov_b32_e32 v38, 0
	v_mov_b32_e32 v39, 0
	v_mov_b32_e32 v40, 0
	v_mov_b32_e32 v41, 0
	v_mov_b32_e32 v42, 0
	v_mov_b32_e32 v43, 0
	v_mov_b32_e32 v44, 0
	v_mov_b32_e32 v45, 0
	v_mov_b32_e32 v46, 0
	v_mov_b32_e32 v47, 0
	v_mov_b32_e32 v48, 0
	v_mov_b32_e32 v49, 0
	v_mov_b32_e32 v50, 0
	v_mov_b32_e32 v51, 0
	v_mov_b32_e32 v52, 0
	v_mov_b32_e32 v53, 0
	v_mov_b32_e32 v54, 0
	v_mov_b32_e32 v55, 0
	v_mov_b32_e32 v56, 0
	v_mov_b32_e32 v57, 0
	v_mov_b32_e32 v58, 0
	v_mov_b32_e32 v59, 0
	v_mov_b32_e32 v60, 0
	v_mov_b32_e32 v61, 0
	v_mov_b32_e32 v62, 0
	v_mov_b32_e32 v63, 0
	v_mov_b32_e32 v64, 0
	v_mov_b32_e32 v65, 0
	v_mov_b32_e32 v66, 0
	v_mov_b32_e32 v67, 0
	v_mov_b32_e32 v68, 0
	v_mov_b32_e32 v69, 0
	v_mov_b32_e32 v70, 0
	v_mov_b32_e32 v71, 0
	v_mov_b32_e32 v72, 0
	v_mov_b32_e32 v73, 0
	v_mov_b32_e32 v74, 0
	v_mov_b32_e32 v75, 0
	v_mov_b32_e32 v76, 0
	v_mov_b32_e32 v77, 0
	v_mov_b32_e32 v78, 0
	v_mov_b32_e32 v79, 0
	v_mov_b32_e32 v80, 0
	v_mov_b32_e32 v81, 0
	v_mov_b32_e32 v82, 0
	v_mov_b32_e32 v83, 0
	v_mov_b32_e32 v84, 0
	v_mov_b32_e32 v85, 0
	v_mov_b32_e32 v86, 0
	v_mov_b32_e32 v87, 0
	v_mov_b32_e32 v88, 0
	v_mov_b32_e32 v89, 0
	v_mov_b32_e32 v90, 0
	v_mov_b32_e32 v91, 0
	v_mov_b32_e32 v92, 0
	v_mov_b32_e32 v93, 0
	v_mov_b32_e32 v94, 0
	v_mov_b32_e32 v95, 0
	v_mov_b32_e32 v96, 0
	v_mov_b32_e32 v97, 0
	v_mov_b32_e32 v98, 0
	v_mov_b32_e32 v99, 0
	v_mov_b32_e32 v100, 0
	v_mov_b32_e32 v101, 0
	v_mov_b32_e32 v102, 0
	v_mov_b32_e32 v103, 0
	v_mov_b32_e32 v104, 0
	v_mov_b32_e32 v105, 0
	v_mov_b32_e32 v106, 0
	v_mov_b32_e32 v107, 0
	v_mov_b32_e32 v108, 0
	v_mov_b32_e32 v109, 0
	v_mov_b32_e32 v110, 0
	v_mov_b32_e32 v111, 0
	v_mov_b32_e32 v112, 0
	v_mov_b32_e32 v113, 0
	v_mov_b32_e32 v114, 0
	v_mov_b32_e32 v115, 0
	v_mov_b32_e32 v116, 0
	v_mov_b32_e32 v117, 0
	v_mov_b32_e32 v118, 0
	v_mov_b32_e32 v119, 0
	v_mov_b32_e32 v120, 0
	v_mov_b32_e32 v121, 0
	v_mov_b32_e32 v122, 0
	v_mov_b32_e32 v123, 0
	v_mov_b32_e32 v124, 0
	v_mov_b32_e32 v125, 0
	v_mov_b32_e32 v126, 0
	v_mov_b32_e32 v127, 0
	v_mov_b32_e32 v128, 0
	v_mov_b32_e32 v129, 0
	s_load_dwordx2 s[56:57], s[12:13], 0x1d0
	v_bfe_u32 v241, v131, 4, 2
	s_lshr_b32 s0, s50, 1
	s_lshl_b32 s0, s0, 6
	s_add_i32 s0, s0, s53
	s_lshl_b32 s0, s0, 2
	v_lshlrev_b32_e32 v241, 4, v241
	s_waitcnt lgkmcnt(0)
	s_add_u32 s56, s56, s0
	s_addc_u32 s57, s57, 0
	global_load_dwordx4 v[152:155], v241, s[56:57]
	global_load_dwordx4 v[244:247], v241, s[56:57] offset:64
	global_load_dwordx4 v[248:251], v241, s[56:57] offset:128
	global_load_dwordx4 v[252:255], v241, s[56:57] offset:192
	s_waitcnt vmcnt(12)
	s_barrier
	s_mov_b32 s52, 0
	v_add_u32_e32 v234, s22, v232
	v_add_u32_e32 v236, s28, v232
	v_add_u32_e32 v235, s22, v233
	v_add_u32_e32 v237, s28, v233
	ds_read_b128 v[136:139], v234
	ds_read_b128 v[140:143], v234 offset:2048
	ds_read_b128 v[144:147], v234 offset:4096
	ds_read_b128 v[148:151], v234 offset:6144
	ds_read_b128 v[188:191], v236
	ds_read_b128 v[196:199], v236 offset:2048
	ds_read_b128 v[200:203], v236 offset:4096
	ds_read_b128 v[204:207], v236 offset:6144
	ds_read_b128 v[172:175], v235
	ds_read_b128 v[176:179], v235 offset:2048
	ds_read_b128 v[180:183], v235 offset:4096
	ds_read_b128 v[184:187], v235 offset:6144
	ds_read_b128 v[212:215], v237
	ds_read_b128 v[216:219], v237 offset:2048
	ds_read_b128 v[220:223], v237 offset:4096
	ds_read_b128 v[224:227], v237 offset:6144
	s_add_i32 m0, s51, 0xc000
	s_nop 0
	global_load_lds_dwordx4 v228, s[44:45]
	s_add_i32 m0, s51, 0xc400
	s_nop 0
	global_load_lds_dwordx4 v230, s[44:45]
	s_add_i32 m0, s51, 0xe000
	s_nop 0
	global_load_lds_dwordx4 v229, s[44:45]
	s_add_i32 m0, s51, 0xe400
	s_nop 0
	global_load_lds_dwordx4 v231, s[44:45]
	s_add_i32 m0, s51, 0x10000
	s_nop 0
	global_load_lds_dwordx4 v228, s[46:47]
	s_add_i32 m0, s51, 0x10400
	s_nop 0
	global_load_lds_dwordx4 v230, s[46:47]
	s_waitcnt lgkmcnt(8)
	s_setprio 1
	v_mfma_f32_16x16x32_bf16 v[2:5], v[136:139], v[188:191], v[2:5]
	v_mfma_f32_16x16x32_bf16 v[6:9], v[136:139], v[196:199], v[6:9]
	v_mfma_f32_16x16x32_bf16 v[10:13], v[136:139], v[200:203], v[10:13]
	v_mfma_f32_16x16x32_bf16 v[14:17], v[136:139], v[204:207], v[14:17]
	v_mfma_f32_16x16x32_bf16 v[18:21], v[140:143], v[188:191], v[18:21]
	v_mfma_f32_16x16x32_bf16 v[22:25], v[140:143], v[196:199], v[22:25]
	v_mfma_f32_16x16x32_bf16 v[26:29], v[140:143], v[200:203], v[26:29]
	v_mfma_f32_16x16x32_bf16 v[30:33], v[140:143], v[204:207], v[30:33]
	v_mfma_f32_16x16x32_bf16 v[34:37], v[144:147], v[188:191], v[34:37]
	v_mfma_f32_16x16x32_bf16 v[38:41], v[144:147], v[196:199], v[38:41]
	v_mfma_f32_16x16x32_bf16 v[42:45], v[144:147], v[200:203], v[42:45]
	v_mfma_f32_16x16x32_bf16 v[46:49], v[144:147], v[204:207], v[46:49]
	v_mfma_f32_16x16x32_bf16 v[50:53], v[148:151], v[188:191], v[50:53]
	v_mfma_f32_16x16x32_bf16 v[54:57], v[148:151], v[196:199], v[54:57]
	v_mfma_f32_16x16x32_bf16 v[58:61], v[148:151], v[200:203], v[58:61]
	v_mfma_f32_16x16x32_bf16 v[62:65], v[148:151], v[204:207], v[62:65]
	s_waitcnt lgkmcnt(0)
	v_mfma_f32_16x16x32_bf16 v[2:5], v[172:175], v[212:215], v[2:5]
	v_mfma_f32_16x16x32_bf16 v[6:9], v[172:175], v[216:219], v[6:9]
	v_mfma_f32_16x16x32_bf16 v[10:13], v[172:175], v[220:223], v[10:13]
	v_mfma_f32_16x16x32_bf16 v[14:17], v[172:175], v[224:227], v[14:17]
	v_mfma_f32_16x16x32_bf16 v[18:21], v[176:179], v[212:215], v[18:21]
	v_mfma_f32_16x16x32_bf16 v[22:25], v[176:179], v[216:219], v[22:25]
	v_mfma_f32_16x16x32_bf16 v[26:29], v[176:179], v[220:223], v[26:29]
	v_mfma_f32_16x16x32_bf16 v[30:33], v[176:179], v[224:227], v[30:33]
	v_mfma_f32_16x16x32_bf16 v[34:37], v[180:183], v[212:215], v[34:37]
	v_mfma_f32_16x16x32_bf16 v[38:41], v[180:183], v[216:219], v[38:41]
	v_mfma_f32_16x16x32_bf16 v[42:45], v[180:183], v[220:223], v[42:45]
	v_mfma_f32_16x16x32_bf16 v[46:49], v[180:183], v[224:227], v[46:49]
	v_mfma_f32_16x16x32_bf16 v[50:53], v[184:187], v[212:215], v[50:53]
	v_mfma_f32_16x16x32_bf16 v[54:57], v[184:187], v[216:219], v[54:57]
	v_mfma_f32_16x16x32_bf16 v[58:61], v[184:187], v[220:223], v[58:61]
	v_mfma_f32_16x16x32_bf16 v[62:65], v[184:187], v[224:227], v[62:65]
	s_setprio 0
	s_waitcnt vmcnt(18)
	s_barrier
	s_branch .Lgu2_loop_a0
.Lgu2_lastp:
	s_add_i32 s21, s21, s72
	s_cmpk_lt_i32 s21, 0x200
	s_cbranch_scc1 .Lgu2_vloop
